# same as V^T b128 version; stores inside the hoisted P2/P9 epilogues converted from flat to global (no flat ops in counted-wait windows)
# speedup vs baseline: 1.0058x; 1.0058x over previous
; DI unsigned pk2(float lo, float hi) { typedef float v2f __attribute__((ext_vector_type(2))); typedef __bf16 v2b __attribute__((ext_vector_type(2))); v2f v = {lo, hi}; v2b b = __builtin_convertvector(v, v2b); return __builtin_bit_cast(unsigned, b); }
; DI float bflo(unsigned w) { return __uint_as_float(w << 16); }
; DI float bfhi(unsigned w) { return __uint_as_float(w & 0xffff0000u); }
; DI void atomic_addf(float* p, float v) { __builtin_amdgcn_global_atomic_fadd_f32((__attribute__((address_space(1))) float*)p, v); }
; DI float quad_sum(float s) { s += __shfl_xor(s, 16); s += __shfl_xor(s, 32); return s; }
;     DI void operator()(const f32x4 (&acc)[2][2][4][2], const Unit& u, int wr, int wc, int fr, int fq) const {
;         const int row0 = u.pm * 256 + wr * 64 + fr, col0 = u.pn * 256 + wc * 32 + 8 * fq;
; #pragma unroll
;         for (int ai = 0; ai < 2; ++ai)
; #pragma unroll
;             for (int m = 0; m < 4; ++m) {
;                 const int row = row0 + ai * 128 + m * 16; float ss = 0.f;
;                 const float bs = (B16 && base) ? base[row] : 1.0f;
; #pragma unroll
;                 for (int bj = 0; bj < 2; ++bj) {
;                     const size_t off = (size_t)row * DM + col0 + bj * 128;
;                     f32x4 b0, b1;
;                     if (B16) { const u32x4 bb = *(const u32x4*)(base16 + off); b0 = (f32x4){bflo(bb.x), bfhi(bb.x), bflo(bb.y), bfhi(bb.y)}; b1 = (f32x4){bflo(bb.z), bfhi(bb.z), bflo(bb.w), bfhi(bb.w)}; b0 = b0 * bs; b1 = b1 * bs; }
;                     else { b0 = *(const f32x4*)(base + off); b1 = *(const f32x4*)(base + off + 4); }
;                     const f32x4 o0 = b0 + acc[ai][bj][m][0] * alpha, o1 = b1 + acc[ai][bj][m][1] * alpha;
;                     if (WOUT) { *(f32x4*)(out + off) = o0; *(f32x4*)(out + off + 4) = o1; }
;                     if (WB) { ss += (o0[0] * o0[0] + o0[1] * o0[1]) + (o0[2] * o0[2] + o0[3] * o0[3]) + (o1[0] * o1[0] + o1[1] * o1[1]) + (o1[2] * o1[2] + o1[3] * o1[3]);
;                         u32x4 w; w.x = pk2(o0[0], o0[1]); w.y = pk2(o0[2], o0[3]); w.z = pk2(o1[0], o1[1]); w.w = pk2(o1[2], o1[3]); *(u32x4*)(xb + off) = w; }
;                 }
;                 if (WB) { ss = quad_sum(ss); if (fq == 0) atomic_addf(P + row, ss); }
;             }
.LBB0_545:
	v_lshl_add_u32 v150, s13, 8, v129
	v_lshl_or_b32 v148, s12, 8, v154
	v_ashrrev_i32_e32 v151, 31, v150
	v_ashrrev_i32_e32 v149, 31, v148
	v_lshlrev_b64 v[152:153], 10, v[150:151]
	v_lshl_add_u64 v[152:153], v[152:153], 0, v[148:149]
	v_lshlrev_b64 v[170:171], 1, v[152:153]
	v_lshl_add_u64 v[152:153], s[14:15], 0, v[170:171]
	v_lshl_add_u64 v[174:175], s[34:35], 0, v[170:171]
	v_mov_b32_e32 v190, v170
	v_mov_b32_e32 v191, v171
	v_lshl_add_u64 v[188:189], v[150:151], 2, s[10:11]
	v_mov_b32_e32 v184, v190
	v_mov_b32_e32 v185, v191
	v_lshl_add_u64 v[186:187], s[14:15], 0, v[184:185]
	global_load_dwordx4 v[198:201], v[186:187], off
	global_load_dwordx4 v[202:205], v[186:187], off offset:256
	global_load_dword v230, v[188:189], off offset:0
	v_add_u32_e32 v184, 0x8000, v190
	v_mov_b32_e32 v185, v191
	v_lshl_add_u64 v[186:187], s[14:15], 0, v[184:185]
	global_load_dwordx4 v[206:209], v[186:187], off
	global_load_dwordx4 v[210:213], v[186:187], off offset:256
	global_load_dword v232, v[188:189], off offset:64
	v_add_u32_e32 v184, 0x10000, v190
	v_mov_b32_e32 v185, v191
	v_lshl_add_u64 v[186:187], s[14:15], 0, v[184:185]
	global_load_dwordx4 v[214:217], v[186:187], off
	global_load_dwordx4 v[218:221], v[186:187], off offset:256
	global_load_dword v234, v[188:189], off offset:128
	v_add_u32_e32 v184, 0x18000, v190
	v_mov_b32_e32 v185, v191
	v_lshl_add_u64 v[186:187], s[14:15], 0, v[184:185]
	global_load_dwordx4 v[222:225], v[186:187], off
	global_load_dwordx4 v[226:229], v[186:187], off offset:256
	global_load_dword v236, v[188:189], off offset:192
	v_or_b32_e32 v170, 0x100, v170
	v_lshl_add_u64 v[160:161], s[14:15], 0, v[170:171]
	s_nop 0
	s_nop 0
	v_lshl_add_u64 v[152:153], v[150:151], 2, s[10:11]
	s_nop 0
	v_and_b32_e32 v160, 64, v158
	v_xor_b32_e32 v159, 16, v158
	v_add_u32_e32 v160, 64, v160
	v_xor_b32_e32 v161, 32, v158
	v_cmp_lt_i32_e32 vcc, v159, v160
	s_waitcnt vmcnt(0)
	v_lshlrev_b32_e32 v176, 16, v198
	v_and_b32_e32 v177, 0xffff0000, v198
	v_lshlrev_b32_e32 v162, 16, v199
	v_and_b32_e32 v163, 0xffff0000, v199
	v_lshlrev_b32_e32 v178, 16, v200
	v_and_b32_e32 v179, 0xffff0000, v200
	v_lshlrev_b32_e32 v164, 16, v201
	v_and_b32_e32 v165, 0xffff0000, v201
	v_pk_mul_f32 v[176:177], v[230:231], v[176:177] op_sel_hi:[0,1]
	v_lshlrev_b32_e32 v180, 16, v202
	v_and_b32_e32 v181, 0xffff0000, v202
	v_lshlrev_b32_e32 v166, 16, v203
	v_and_b32_e32 v167, 0xffff0000, v203
	v_cndmask_b32_e32 v159, v158, v159, vcc
	v_cmp_lt_i32_e32 vcc, v161, v160
	v_pk_mul_f32 v[162:163], v[230:231], v[162:163] op_sel_hi:[0,1]
	v_pk_mul_f32 v[178:179], v[230:231], v[178:179] op_sel_hi:[0,1]
	v_pk_mul_f32 v[164:165], v[230:231], v[164:165] op_sel_hi:[0,1]
	v_lshlrev_b32_e32 v182, 16, v204
	v_and_b32_e32 v183, 0xffff0000, v204
	v_lshlrev_b32_e32 v168, 16, v205
	v_and_b32_e32 v169, 0xffff0000, v205
	v_pk_fma_f32 v[124:125], v[124:125], 0.5, v[176:177] op_sel_hi:[1,0,1]
	v_pk_mul_f32 v[176:177], v[230:231], v[180:181] op_sel_hi:[0,1]
	v_pk_mul_f32 v[166:167], v[230:231], v[166:167] op_sel_hi:[0,1]
	v_cndmask_b32_e32 v161, v158, v161, vcc
	v_pk_fma_f32 v[126:127], v[126:127], 0.5, v[162:163] op_sel_hi:[1,0,1]
	v_pk_fma_f32 v[162:163], v[122:123], 0.5, v[164:165] op_sel_hi:[1,0,1]
	v_pk_fma_f32 v[164:165], v[120:121], 0.5, v[178:179] op_sel_hi:[1,0,1]
	v_pk_mul_f32 v[178:179], v[230:231], v[182:183] op_sel_hi:[0,1]
	v_pk_mul_f32 v[168:169], v[230:231], v[168:169] op_sel_hi:[0,1]
	v_pk_fma_f32 v[118:119], v[118:119], 0.5, v[166:167] op_sel_hi:[1,0,1]
	v_pk_fma_f32 v[116:117], v[116:117], 0.5, v[176:177] op_sel_hi:[1,0,1]
	v_lshlrev_b32_e32 v160, 2, v159
	v_lshlrev_b32_e32 v159, 2, v161
	v_mul_f32_e32 v123, v125, v125
	v_mul_f32_e32 v161, v127, v127
	v_pk_fma_f32 v[166:167], v[114:115], 0.5, v[168:169] op_sel_hi:[1,0,1]
	v_pk_fma_f32 v[168:169], v[112:113], 0.5, v[178:179] op_sel_hi:[1,0,1]
	v_mul_f32_e32 v112, v117, v117
	v_mul_f32_e32 v113, v119, v119
	v_mul_f32_e32 v172, v165, v165
	v_fmac_f32_e32 v123, v124, v124
	v_fmac_f32_e32 v161, v126, v126
	v_mul_f32_e32 v114, v169, v169
	v_fmac_f32_e32 v112, v116, v116
	v_fmac_f32_e32 v113, v118, v118
	v_mul_f32_e32 v173, v163, v163
	v_fmac_f32_e32 v172, v164, v164
	v_mul_f32_e32 v115, v167, v167
	v_add_f32_e32 v123, v123, v161
	v_fmac_f32_e32 v114, v168, v168
	v_add_f32_e32 v112, v112, v113
	v_fmac_f32_e32 v173, v162, v162
	v_add_f32_e32 v123, v172, v123
	v_add_f32_e32 v112, v114, v112
	v_fmac_f32_e32 v115, v166, v166
	v_add_f32_e32 v113, v173, v123
	v_add_f32_e32 v112, v115, v112
	v_add_f32_e32 v112, v113, v112
	ds_bpermute_b32 v113, v160, v112
	v_cvt_pk_bf16_f32 v120, v124, v125
	v_cvt_pk_bf16_f32 v121, v126, v127
	v_cvt_pk_bf16_f32 v122, v164, v165
	v_cvt_pk_bf16_f32 v123, v162, v163
	s_waitcnt lgkmcnt(0)
	v_add_f32_e32 v112, v112, v113
	ds_bpermute_b32 v113, v159, v112
	v_cvt_pk_bf16_f32 v114, v116, v117
	v_cvt_pk_bf16_f32 v115, v118, v119
	v_cvt_pk_bf16_f32 v116, v168, v169
	v_cvt_pk_bf16_f32 v117, v166, v167
	v_lshl_add_u64 v[118:119], s[34:35], 0, v[170:171]
	global_store_dwordx4 v[174:175], v[120:123], off
	global_store_dwordx4 v[118:119], v[114:117], off
	s_and_saveexec_b64 s[12:13], s[2:3]
	v_readlane_b32 s88, v249, 57
	v_readlane_b32 s89, v249, 58
	s_cbranch_execz .LBB0_547
	v_lshl_add_u64 v[114:115], v[150:151], 2, s[42:43]
	s_waitcnt lgkmcnt(0)
	v_add_f32_e32 v112, v112, v113
	global_atomic_add_f32 v[114:115], v112, off
; DI unsigned pk2(float lo, float hi) { typedef float v2f __attribute__((ext_vector_type(2))); typedef __bf16 v2b __attribute__((ext_vector_type(2))); v2f v = {lo, hi}; v2b b = __builtin_convertvector(v, v2b); return __builtin_bit_cast(unsigned, b); }
; DI float bflo(unsigned w) { return __uint_as_float(w << 16); }
; DI float bfhi(unsigned w) { return __uint_as_float(w & 0xffff0000u); }
; DI void atomic_addf(float* p, float v) { __builtin_amdgcn_global_atomic_fadd_f32((__attribute__((address_space(1))) float*)p, v); }
; DI float quad_sum(float s) { s += __shfl_xor(s, 16); s += __shfl_xor(s, 32); return s; }
;     DI void operator()(const f32x4 (&acc)[2][2][4][2], const Unit& u, int wr, int wc, int fr, int fq) const {
;         const int row0 = u.pm * 256 + wr * 64 + fr, col0 = u.pn * 256 + wc * 32 + 8 * fq;
; #pragma unroll
;         for (int ai = 0; ai < 2; ++ai)
; #pragma unroll
;             for (int m = 0; m < 4; ++m) {
;                 const int row = row0 + ai * 128 + m * 16; float ss = 0.f;
;                 const float bs = (B16 && base) ? base[row] : 1.0f;
; #pragma unroll
;                 for (int bj = 0; bj < 2; ++bj) {
;                     const size_t off = (size_t)row * DM + col0 + bj * 128;
;                     f32x4 b0, b1;
;                     if (B16) { const u32x4 bb = *(const u32x4*)(base16 + off); b0 = (f32x4){bflo(bb.x), bfhi(bb.x), bflo(bb.y), bfhi(bb.y)}; b1 = (f32x4){bflo(bb.z), bfhi(bb.z), bflo(bb.w), bfhi(bb.w)}; b0 = b0 * bs; b1 = b1 * bs; }
;                     else { b0 = *(const f32x4*)(base + off); b1 = *(const f32x4*)(base + off + 4); }
;                     const f32x4 o0 = b0 + acc[ai][bj][m][0] * alpha, o1 = b1 + acc[ai][bj][m][1] * alpha;
;                     if (WOUT) { *(f32x4*)(out + off) = o0; *(f32x4*)(out + off + 4) = o1; }
;                     if (WB) { ss += (o0[0] * o0[0] + o0[1] * o0[1]) + (o0[2] * o0[2] + o0[3] * o0[3]) + (o1[0] * o1[0] + o1[1] * o1[1]) + (o1[2] * o1[2] + o1[3] * o1[3]);
;                         u32x4 w; w.x = pk2(o0[0], o0[1]); w.y = pk2(o0[2], o0[3]); w.z = pk2(o1[0], o1[1]); w.w = pk2(o1[2], o1[3]); *(u32x4*)(xb + off) = w; }
;                 }
;                 if (WB) { ss = quad_sum(ss); if (fq == 0) atomic_addf(P + row, ss); }
;             }
.LBB0_547:
	s_or_b64 exec, exec, s[12:13]
	v_or_b32_e32 v112, 16, v150
	s_waitcnt lgkmcnt(0)
	v_ashrrev_i32_e32 v113, 31, v112
	v_lshlrev_b64 v[114:115], 10, v[112:113]
	v_lshl_add_u64 v[114:115], v[114:115], 0, v[148:149]
	v_lshlrev_b64 v[122:123], 1, v[114:115]
	v_lshl_add_u64 v[114:115], s[14:15], 0, v[122:123]
	v_lshl_add_u64 v[118:119], v[112:113], 2, s[10:11]
	v_lshl_add_u64 v[126:127], s[34:35], 0, v[122:123]
	v_or_b32_e32 v122, 0x100, v122
	s_nop 0
	s_nop 0
	s_nop 0
	v_lshl_add_u64 v[118:119], s[14:15], 0, v[122:123]
	s_nop 0
	v_lshlrev_b32_e32 v162, 16, v206
	v_and_b32_e32 v163, 0xffff0000, v206
	v_lshlrev_b32_e32 v114, 16, v207
	v_and_b32_e32 v115, 0xffff0000, v207
	v_lshlrev_b32_e32 v164, 16, v208
	v_and_b32_e32 v165, 0xffff0000, v208
	v_lshlrev_b32_e32 v116, 16, v209
	v_and_b32_e32 v117, 0xffff0000, v209
	v_pk_mul_f32 v[162:163], v[232:233], v[162:163] op_sel_hi:[0,1]
	v_lshlrev_b32_e32 v166, 16, v210
	v_and_b32_e32 v167, 0xffff0000, v210
	v_lshlrev_b32_e32 v118, 16, v211
	v_and_b32_e32 v119, 0xffff0000, v211
	v_pk_mul_f32 v[114:115], v[232:233], v[114:115] op_sel_hi:[0,1]
	v_pk_mul_f32 v[164:165], v[232:233], v[164:165] op_sel_hi:[0,1]
	v_pk_mul_f32 v[116:117], v[232:233], v[116:117] op_sel_hi:[0,1]
	v_lshlrev_b32_e32 v168, 16, v212
	v_and_b32_e32 v169, 0xffff0000, v212
	v_lshlrev_b32_e32 v120, 16, v213
	v_and_b32_e32 v121, 0xffff0000, v213
	v_pk_fma_f32 v[108:109], v[108:109], 0.5, v[162:163] op_sel_hi:[1,0,1]
	v_pk_mul_f32 v[162:163], v[232:233], v[166:167] op_sel_hi:[0,1]
	v_pk_mul_f32 v[118:119], v[232:233], v[118:119] op_sel_hi:[0,1]
	v_pk_fma_f32 v[110:111], v[110:111], 0.5, v[114:115] op_sel_hi:[1,0,1]
	v_pk_fma_f32 v[114:115], v[106:107], 0.5, v[116:117] op_sel_hi:[1,0,1]
	v_pk_fma_f32 v[116:117], v[104:105], 0.5, v[164:165] op_sel_hi:[1,0,1]
	v_pk_mul_f32 v[164:165], v[232:233], v[168:169] op_sel_hi:[0,1]
	v_pk_mul_f32 v[120:121], v[232:233], v[120:121] op_sel_hi:[0,1]
	v_pk_fma_f32 v[102:103], v[102:103], 0.5, v[118:119] op_sel_hi:[1,0,1]
	v_pk_fma_f32 v[100:101], v[100:101], 0.5, v[162:163] op_sel_hi:[1,0,1]
	v_mul_f32_e32 v107, v109, v109
	v_mul_f32_e32 v124, v111, v111
	v_pk_fma_f32 v[118:119], v[98:99], 0.5, v[120:121] op_sel_hi:[1,0,1]
	v_pk_fma_f32 v[120:121], v[96:97], 0.5, v[164:165] op_sel_hi:[1,0,1]
	v_mul_f32_e32 v96, v101, v101
	v_mul_f32_e32 v97, v103, v103
	v_mul_f32_e32 v125, v117, v117
	v_fmac_f32_e32 v107, v108, v108
	v_fmac_f32_e32 v124, v110, v110
	v_mul_f32_e32 v98, v121, v121
	v_fmac_f32_e32 v96, v100, v100
	v_fmac_f32_e32 v97, v102, v102
	v_mul_f32_e32 v151, v115, v115
	v_fmac_f32_e32 v125, v116, v116
	v_mul_f32_e32 v99, v119, v119
	v_add_f32_e32 v107, v107, v124
	v_fmac_f32_e32 v98, v120, v120
	v_add_f32_e32 v96, v96, v97
	v_fmac_f32_e32 v151, v114, v114
	v_add_f32_e32 v107, v125, v107
	v_add_f32_e32 v96, v98, v96
	v_fmac_f32_e32 v99, v118, v118
	v_add_f32_e32 v97, v151, v107
	v_add_f32_e32 v96, v99, v96
	v_add_f32_e32 v96, v97, v96
	ds_bpermute_b32 v97, v160, v96
	v_cvt_pk_bf16_f32 v104, v108, v109
	v_cvt_pk_bf16_f32 v105, v110, v111
	v_cvt_pk_bf16_f32 v106, v116, v117
	v_cvt_pk_bf16_f32 v107, v114, v115
	s_waitcnt lgkmcnt(0)
	v_add_f32_e32 v96, v96, v97
	ds_bpermute_b32 v97, v159, v96
	v_cvt_pk_bf16_f32 v98, v100, v101
	v_cvt_pk_bf16_f32 v99, v102, v103
	v_cvt_pk_bf16_f32 v100, v120, v121
	v_cvt_pk_bf16_f32 v101, v118, v119
	v_lshl_add_u64 v[102:103], s[34:35], 0, v[122:123]
	global_store_dwordx4 v[126:127], v[104:107], off
	global_store_dwordx4 v[102:103], v[98:101], off
	s_and_saveexec_b64 s[12:13], s[2:3]
	s_cbranch_execz .LBB0_549
	v_lshl_add_u64 v[98:99], v[112:113], 2, s[42:43]
	s_waitcnt lgkmcnt(0)
	v_add_f32_e32 v96, v96, v97
	global_atomic_add_f32 v[98:99], v96, off
.LBB0_549:
	s_or_b64 exec, exec, s[12:13]
	v_or_b32_e32 v96, 32, v150
	s_waitcnt lgkmcnt(0)
	v_ashrrev_i32_e32 v97, 31, v96
	v_lshlrev_b64 v[98:99], 10, v[96:97]
	v_lshl_add_u64 v[98:99], v[98:99], 0, v[148:149]
	v_lshlrev_b64 v[106:107], 1, v[98:99]
	v_lshl_add_u64 v[98:99], s[14:15], 0, v[106:107]
	v_lshl_add_u64 v[102:103], v[96:97], 2, s[10:11]
	v_lshl_add_u64 v[110:111], s[34:35], 0, v[106:107]
	v_or_b32_e32 v106, 0x100, v106
	s_nop 0
	s_nop 0
	s_nop 0
	v_lshl_add_u64 v[102:103], s[14:15], 0, v[106:107]
	s_nop 0
	v_lshlrev_b32_e32 v112, 16, v214
	v_and_b32_e32 v113, 0xffff0000, v214
	v_lshlrev_b32_e32 v98, 16, v215
	v_and_b32_e32 v99, 0xffff0000, v215
	v_lshlrev_b32_e32 v114, 16, v216
	v_and_b32_e32 v115, 0xffff0000, v216
	v_lshlrev_b32_e32 v100, 16, v217
	v_and_b32_e32 v101, 0xffff0000, v217
	v_pk_mul_f32 v[112:113], v[234:235], v[112:113] op_sel_hi:[0,1]
	v_lshlrev_b32_e32 v116, 16, v218
	v_and_b32_e32 v117, 0xffff0000, v218
	v_lshlrev_b32_e32 v102, 16, v219
	v_and_b32_e32 v103, 0xffff0000, v219
	v_pk_mul_f32 v[98:99], v[234:235], v[98:99] op_sel_hi:[0,1]
	v_pk_mul_f32 v[114:115], v[234:235], v[114:115] op_sel_hi:[0,1]
	v_pk_mul_f32 v[100:101], v[234:235], v[100:101] op_sel_hi:[0,1]
	v_lshlrev_b32_e32 v118, 16, v220
	v_and_b32_e32 v119, 0xffff0000, v220
	v_lshlrev_b32_e32 v104, 16, v221
	v_and_b32_e32 v105, 0xffff0000, v221
	v_pk_fma_f32 v[92:93], v[92:93], 0.5, v[112:113] op_sel_hi:[1,0,1]
	v_pk_mul_f32 v[112:113], v[234:235], v[116:117] op_sel_hi:[0,1]
	v_pk_mul_f32 v[102:103], v[234:235], v[102:103] op_sel_hi:[0,1]
	v_pk_fma_f32 v[94:95], v[94:95], 0.5, v[98:99] op_sel_hi:[1,0,1]
	v_pk_fma_f32 v[98:99], v[90:91], 0.5, v[100:101] op_sel_hi:[1,0,1]
	v_pk_fma_f32 v[100:101], v[88:89], 0.5, v[114:115] op_sel_hi:[1,0,1]
	v_pk_mul_f32 v[114:115], v[234:235], v[118:119] op_sel_hi:[0,1]
	v_pk_mul_f32 v[104:105], v[234:235], v[104:105] op_sel_hi:[0,1]
	v_pk_fma_f32 v[86:87], v[86:87], 0.5, v[102:103] op_sel_hi:[1,0,1]
	v_pk_fma_f32 v[84:85], v[84:85], 0.5, v[112:113] op_sel_hi:[1,0,1]
	v_mul_f32_e32 v91, v93, v93
	v_mul_f32_e32 v108, v95, v95
	v_pk_fma_f32 v[102:103], v[82:83], 0.5, v[104:105] op_sel_hi:[1,0,1]
	v_pk_fma_f32 v[104:105], v[80:81], 0.5, v[114:115] op_sel_hi:[1,0,1]
	v_mul_f32_e32 v80, v85, v85
	v_mul_f32_e32 v81, v87, v87
	v_mul_f32_e32 v109, v101, v101
	v_fmac_f32_e32 v91, v92, v92
	v_fmac_f32_e32 v108, v94, v94
	v_mul_f32_e32 v82, v105, v105
	v_fmac_f32_e32 v80, v84, v84
	v_fmac_f32_e32 v81, v86, v86
	v_mul_f32_e32 v116, v99, v99
	v_fmac_f32_e32 v109, v100, v100
	v_mul_f32_e32 v83, v103, v103
	v_add_f32_e32 v91, v91, v108
	v_fmac_f32_e32 v82, v104, v104
	v_add_f32_e32 v80, v80, v81
	v_fmac_f32_e32 v116, v98, v98
	v_add_f32_e32 v91, v109, v91
	v_add_f32_e32 v80, v82, v80
	v_fmac_f32_e32 v83, v102, v102
	v_add_f32_e32 v81, v116, v91
	v_add_f32_e32 v80, v83, v80
	v_add_f32_e32 v80, v81, v80
	ds_bpermute_b32 v81, v160, v80
	v_cvt_pk_bf16_f32 v88, v92, v93
	v_cvt_pk_bf16_f32 v89, v94, v95
	v_cvt_pk_bf16_f32 v90, v100, v101
	v_cvt_pk_bf16_f32 v91, v98, v99
	s_waitcnt lgkmcnt(0)
; DI unsigned pk2(float lo, float hi) { typedef float v2f __attribute__((ext_vector_type(2))); typedef __bf16 v2b __attribute__((ext_vector_type(2))); v2f v = {lo, hi}; v2b b = __builtin_convertvector(v, v2b); return __builtin_bit_cast(unsigned, b); }
; DI float bflo(unsigned w) { return __uint_as_float(w << 16); }
; DI float bfhi(unsigned w) { return __uint_as_float(w & 0xffff0000u); }
; DI void atomic_addf(float* p, float v) { __builtin_amdgcn_global_atomic_fadd_f32((__attribute__((address_space(1))) float*)p, v); }
; DI float quad_sum(float s) { s += __shfl_xor(s, 16); s += __shfl_xor(s, 32); return s; }
;     DI void operator()(const f32x4 (&acc)[2][2][4][2], const Unit& u, int wr, int wc, int fr, int fq) const {
;         const int row0 = u.pm * 256 + wr * 64 + fr, col0 = u.pn * 256 + wc * 32 + 8 * fq;
; #pragma unroll
;         for (int ai = 0; ai < 2; ++ai)
; #pragma unroll
;             for (int m = 0; m < 4; ++m) {
;                 const int row = row0 + ai * 128 + m * 16; float ss = 0.f;
;                 const float bs = (B16 && base) ? base[row] : 1.0f;
; #pragma unroll
;                 for (int bj = 0; bj < 2; ++bj) {
;                     const size_t off = (size_t)row * DM + col0 + bj * 128;
;                     f32x4 b0, b1;
;                     if (B16) { const u32x4 bb = *(const u32x4*)(base16 + off); b0 = (f32x4){bflo(bb.x), bfhi(bb.x), bflo(bb.y), bfhi(bb.y)}; b1 = (f32x4){bflo(bb.z), bfhi(bb.z), bflo(bb.w), bfhi(bb.w)}; b0 = b0 * bs; b1 = b1 * bs; }
;                     else { b0 = *(const f32x4*)(base + off); b1 = *(const f32x4*)(base + off + 4); }
;                     const f32x4 o0 = b0 + acc[ai][bj][m][0] * alpha, o1 = b1 + acc[ai][bj][m][1] * alpha;
;                     if (WOUT) { *(f32x4*)(out + off) = o0; *(f32x4*)(out + off + 4) = o1; }
;                     if (WB) { ss += (o0[0] * o0[0] + o0[1] * o0[1]) + (o0[2] * o0[2] + o0[3] * o0[3]) + (o1[0] * o1[0] + o1[1] * o1[1]) + (o1[2] * o1[2] + o1[3] * o1[3]);
;                         u32x4 w; w.x = pk2(o0[0], o0[1]); w.y = pk2(o0[2], o0[3]); w.z = pk2(o1[0], o1[1]); w.w = pk2(o1[2], o1[3]); *(u32x4*)(xb + off) = w; }
;                 }
;                 if (WB) { ss = quad_sum(ss); if (fq == 0) atomic_addf(P + row, ss); }
;             }
	v_add_f32_e32 v80, v80, v81
	ds_bpermute_b32 v81, v159, v80
	v_cvt_pk_bf16_f32 v82, v84, v85
	v_cvt_pk_bf16_f32 v83, v86, v87
	v_cvt_pk_bf16_f32 v84, v104, v105
	v_cvt_pk_bf16_f32 v85, v102, v103
	v_lshl_add_u64 v[86:87], s[34:35], 0, v[106:107]
	global_store_dwordx4 v[110:111], v[88:91], off
	global_store_dwordx4 v[86:87], v[82:85], off
	s_and_saveexec_b64 s[12:13], s[2:3]
	s_cbranch_execz .LBB0_551
	v_lshl_add_u64 v[82:83], v[96:97], 2, s[42:43]
	s_waitcnt lgkmcnt(0)
	v_add_f32_e32 v80, v80, v81
	global_atomic_add_f32 v[82:83], v80, off
.LBB0_551:
	s_or_b64 exec, exec, s[12:13]
	v_or_b32_e32 v80, 48, v150
	s_waitcnt lgkmcnt(0)
	v_ashrrev_i32_e32 v81, 31, v80
	v_lshlrev_b64 v[82:83], 10, v[80:81]
	v_lshl_add_u64 v[82:83], v[82:83], 0, v[148:149]
	v_lshlrev_b64 v[90:91], 1, v[82:83]
	v_lshl_add_u64 v[82:83], s[14:15], 0, v[90:91]
	v_lshl_add_u64 v[86:87], v[80:81], 2, s[10:11]
	v_lshl_add_u64 v[94:95], s[34:35], 0, v[90:91]
	v_or_b32_e32 v90, 0x100, v90
	s_nop 0
	s_nop 0
	s_nop 0
	v_lshl_add_u64 v[86:87], s[14:15], 0, v[90:91]
	s_nop 0
	v_lshlrev_b32_e32 v96, 16, v222
	v_and_b32_e32 v97, 0xffff0000, v222
	v_lshlrev_b32_e32 v82, 16, v223
	v_and_b32_e32 v83, 0xffff0000, v223
	v_lshlrev_b32_e32 v98, 16, v224
	v_and_b32_e32 v99, 0xffff0000, v224
	v_lshlrev_b32_e32 v84, 16, v225
	v_and_b32_e32 v85, 0xffff0000, v225
	v_pk_mul_f32 v[96:97], v[236:237], v[96:97] op_sel_hi:[0,1]
	v_lshlrev_b32_e32 v100, 16, v226
	v_and_b32_e32 v101, 0xffff0000, v226
	v_lshlrev_b32_e32 v86, 16, v227
	v_and_b32_e32 v87, 0xffff0000, v227
	v_pk_mul_f32 v[82:83], v[236:237], v[82:83] op_sel_hi:[0,1]
	v_pk_mul_f32 v[98:99], v[236:237], v[98:99] op_sel_hi:[0,1]
	v_pk_mul_f32 v[84:85], v[236:237], v[84:85] op_sel_hi:[0,1]
	v_lshlrev_b32_e32 v102, 16, v228
	v_and_b32_e32 v103, 0xffff0000, v228
	v_lshlrev_b32_e32 v88, 16, v229
	v_and_b32_e32 v89, 0xffff0000, v229
	v_pk_fma_f32 v[76:77], v[76:77], 0.5, v[96:97] op_sel_hi:[1,0,1]
	v_pk_mul_f32 v[96:97], v[236:237], v[100:101] op_sel_hi:[0,1]
	v_pk_mul_f32 v[86:87], v[236:237], v[86:87] op_sel_hi:[0,1]
	v_pk_fma_f32 v[78:79], v[78:79], 0.5, v[82:83] op_sel_hi:[1,0,1]
	v_pk_fma_f32 v[82:83], v[74:75], 0.5, v[84:85] op_sel_hi:[1,0,1]
	v_pk_fma_f32 v[84:85], v[72:73], 0.5, v[98:99] op_sel_hi:[1,0,1]
	v_pk_mul_f32 v[98:99], v[236:237], v[102:103] op_sel_hi:[0,1]
	v_pk_mul_f32 v[88:89], v[236:237], v[88:89] op_sel_hi:[0,1]
	v_add_u32_e32 v184, 0x40000, v190
	v_mov_b32_e32 v185, v191
	v_lshl_add_u64 v[186:187], s[14:15], 0, v[184:185]
	global_load_dwordx4 v[198:201], v[186:187], off
	global_load_dwordx4 v[202:205], v[186:187], off offset:256
	global_load_dword v230, v[188:189], off offset:512
	v_add_u32_e32 v184, 0x48000, v190
	v_mov_b32_e32 v185, v191
	v_lshl_add_u64 v[186:187], s[14:15], 0, v[184:185]
	global_load_dwordx4 v[206:209], v[186:187], off
	global_load_dwordx4 v[210:213], v[186:187], off offset:256
	global_load_dword v232, v[188:189], off offset:576
	v_add_u32_e32 v184, 0x50000, v190
	v_mov_b32_e32 v185, v191
	v_lshl_add_u64 v[186:187], s[14:15], 0, v[184:185]
	global_load_dwordx4 v[214:217], v[186:187], off
	global_load_dwordx4 v[218:221], v[186:187], off offset:256
	global_load_dword v234, v[188:189], off offset:640
	v_add_u32_e32 v184, 0x58000, v190
	v_mov_b32_e32 v185, v191
	v_lshl_add_u64 v[186:187], s[14:15], 0, v[184:185]
	global_load_dwordx4 v[222:225], v[186:187], off
	global_load_dwordx4 v[226:229], v[186:187], off offset:256
	global_load_dword v236, v[188:189], off offset:704
	v_pk_fma_f32 v[70:71], v[70:71], 0.5, v[86:87] op_sel_hi:[1,0,1]
	v_pk_fma_f32 v[68:69], v[68:69], 0.5, v[96:97] op_sel_hi:[1,0,1]
	v_mul_f32_e32 v75, v77, v77
	v_mul_f32_e32 v92, v79, v79
	v_pk_fma_f32 v[86:87], v[66:67], 0.5, v[88:89] op_sel_hi:[1,0,1]
	v_pk_fma_f32 v[88:89], v[64:65], 0.5, v[98:99] op_sel_hi:[1,0,1]
	v_mul_f32_e32 v64, v69, v69
	v_mul_f32_e32 v65, v71, v71
	v_mul_f32_e32 v93, v85, v85
	v_fmac_f32_e32 v75, v76, v76
	v_fmac_f32_e32 v92, v78, v78
	v_mul_f32_e32 v66, v89, v89
	v_fmac_f32_e32 v64, v68, v68
	v_fmac_f32_e32 v65, v70, v70
	v_mul_f32_e32 v100, v83, v83
	v_fmac_f32_e32 v93, v84, v84
	v_mul_f32_e32 v67, v87, v87
	v_add_f32_e32 v75, v75, v92
	v_fmac_f32_e32 v66, v88, v88
	v_add_f32_e32 v64, v64, v65
	v_fmac_f32_e32 v100, v82, v82
	v_add_f32_e32 v75, v93, v75
	v_add_f32_e32 v64, v66, v64
	v_fmac_f32_e32 v67, v86, v86
	v_add_f32_e32 v65, v100, v75
	v_add_f32_e32 v64, v67, v64
	v_add_f32_e32 v64, v65, v64
	ds_bpermute_b32 v65, v160, v64
	v_cvt_pk_bf16_f32 v72, v76, v77
	v_cvt_pk_bf16_f32 v73, v78, v79
	v_cvt_pk_bf16_f32 v74, v84, v85
	v_cvt_pk_bf16_f32 v75, v82, v83
	s_waitcnt lgkmcnt(0)
	v_add_f32_e32 v64, v64, v65
	ds_bpermute_b32 v65, v159, v64
	v_cvt_pk_bf16_f32 v66, v68, v69
	v_cvt_pk_bf16_f32 v67, v70, v71
	v_cvt_pk_bf16_f32 v68, v88, v89
	v_cvt_pk_bf16_f32 v69, v86, v87
	v_lshl_add_u64 v[70:71], s[34:35], 0, v[90:91]
	global_store_dwordx4 v[94:95], v[72:75], off
	global_store_dwordx4 v[70:71], v[66:69], off
	s_and_saveexec_b64 s[12:13], s[2:3]
	s_cbranch_execz .LBB0_553
	v_lshl_add_u64 v[66:67], v[80:81], 2, s[42:43]
	s_waitcnt lgkmcnt(0)
	v_add_f32_e32 v64, v64, v65
	global_atomic_add_f32 v[66:67], v64, off
; DI unsigned pk2(float lo, float hi) { typedef float v2f __attribute__((ext_vector_type(2))); typedef __bf16 v2b __attribute__((ext_vector_type(2))); v2f v = {lo, hi}; v2b b = __builtin_convertvector(v, v2b); return __builtin_bit_cast(unsigned, b); }
; DI float bflo(unsigned w) { return __uint_as_float(w << 16); }
; DI float bfhi(unsigned w) { return __uint_as_float(w & 0xffff0000u); }
; DI void atomic_addf(float* p, float v) { __builtin_amdgcn_global_atomic_fadd_f32((__attribute__((address_space(1))) float*)p, v); }
; DI float quad_sum(float s) { s += __shfl_xor(s, 16); s += __shfl_xor(s, 32); return s; }
;     DI void operator()(const f32x4 (&acc)[2][2][4][2], const Unit& u, int wr, int wc, int fr, int fq) const {
;         const int row0 = u.pm * 256 + wr * 64 + fr, col0 = u.pn * 256 + wc * 32 + 8 * fq;
; #pragma unroll
;         for (int ai = 0; ai < 2; ++ai)
; #pragma unroll
;             for (int m = 0; m < 4; ++m) {
;                 const int row = row0 + ai * 128 + m * 16; float ss = 0.f;
;                 const float bs = (B16 && base) ? base[row] : 1.0f;
; #pragma unroll
;                 for (int bj = 0; bj < 2; ++bj) {
;                     const size_t off = (size_t)row * DM + col0 + bj * 128;
;                     f32x4 b0, b1;
;                     if (B16) { const u32x4 bb = *(const u32x4*)(base16 + off); b0 = (f32x4){bflo(bb.x), bfhi(bb.x), bflo(bb.y), bfhi(bb.y)}; b1 = (f32x4){bflo(bb.z), bfhi(bb.z), bflo(bb.w), bfhi(bb.w)}; b0 = b0 * bs; b1 = b1 * bs; }
;                     else { b0 = *(const f32x4*)(base + off); b1 = *(const f32x4*)(base + off + 4); }
;                     const f32x4 o0 = b0 + acc[ai][bj][m][0] * alpha, o1 = b1 + acc[ai][bj][m][1] * alpha;
;                     if (WOUT) { *(f32x4*)(out + off) = o0; *(f32x4*)(out + off + 4) = o1; }
;                     if (WB) { ss += (o0[0] * o0[0] + o0[1] * o0[1]) + (o0[2] * o0[2] + o0[3] * o0[3]) + (o1[0] * o1[0] + o1[1] * o1[1]) + (o1[2] * o1[2] + o1[3] * o1[3]);
;                         u32x4 w; w.x = pk2(o0[0], o0[1]); w.y = pk2(o0[2], o0[3]); w.z = pk2(o1[0], o1[1]); w.w = pk2(o1[2], o1[3]); *(u32x4*)(xb + off) = w; }
;                 }
;                 if (WB) { ss = quad_sum(ss); if (fq == 0) atomic_addf(P + row, ss); }
;             }
.LBB0_553:
	s_or_b64 exec, exec, s[12:13]
	v_add_u32_e32 v64, 0x80, v150
	s_waitcnt lgkmcnt(0)
	v_ashrrev_i32_e32 v65, 31, v64
	v_lshlrev_b64 v[66:67], 10, v[64:65]
	v_lshl_add_u64 v[66:67], v[66:67], 0, v[148:149]
	v_lshlrev_b64 v[74:75], 1, v[66:67]
	v_lshl_add_u64 v[66:67], s[14:15], 0, v[74:75]
	v_lshl_add_u64 v[78:79], s[34:35], 0, v[74:75]
	v_or_b32_e32 v74, 0x100, v74
	v_lshl_add_u64 v[70:71], s[14:15], 0, v[74:75]
	s_nop 0
	s_nop 0
	s_nop 0
	s_waitcnt vmcnt(2)
	v_lshlrev_b32_e32 v80, 16, v198
	s_nop 0
	v_and_b32_e32 v81, 0xffff0000, v198
	v_lshlrev_b32_e32 v66, 16, v199
	v_and_b32_e32 v67, 0xffff0000, v199
	v_lshlrev_b32_e32 v82, 16, v200
	v_and_b32_e32 v83, 0xffff0000, v200
	v_lshlrev_b32_e32 v68, 16, v201
	v_and_b32_e32 v69, 0xffff0000, v201
	v_pk_mul_f32 v[80:81], v[230:231], v[80:81] op_sel_hi:[0,1]
	v_pk_mul_f32 v[66:67], v[230:231], v[66:67] op_sel_hi:[0,1]
	v_pk_mul_f32 v[82:83], v[230:231], v[82:83] op_sel_hi:[0,1]
	v_pk_mul_f32 v[68:69], v[230:231], v[68:69] op_sel_hi:[0,1]
	v_pk_fma_f32 v[60:61], v[60:61], 0.5, v[80:81] op_sel_hi:[1,0,1]
	v_pk_fma_f32 v[62:63], v[62:63], 0.5, v[66:67] op_sel_hi:[1,0,1]
	v_pk_fma_f32 v[66:67], v[58:59], 0.5, v[68:69] op_sel_hi:[1,0,1]
	v_pk_fma_f32 v[68:69], v[56:57], 0.5, v[82:83] op_sel_hi:[1,0,1]
	v_mul_f32_e32 v59, v61, v61
	v_fmac_f32_e32 v59, v60, v60
	v_cvt_pk_bf16_f32 v56, v60, v61
	v_cvt_pk_bf16_f32 v57, v62, v63
	v_cvt_pk_bf16_f32 v58, v68, v69
	v_lshlrev_b32_e32 v84, 16, v202
	v_and_b32_e32 v85, 0xffff0000, v202
	v_lshlrev_b32_e32 v70, 16, v203
	v_and_b32_e32 v71, 0xffff0000, v203
	v_lshlrev_b32_e32 v86, 16, v204
	v_and_b32_e32 v87, 0xffff0000, v204
	v_lshlrev_b32_e32 v72, 16, v205
	v_and_b32_e32 v73, 0xffff0000, v205
	v_pk_mul_f32 v[80:81], v[230:231], v[84:85] op_sel_hi:[0,1]
	v_pk_mul_f32 v[70:71], v[230:231], v[70:71] op_sel_hi:[0,1]
	v_pk_mul_f32 v[82:83], v[230:231], v[86:87] op_sel_hi:[0,1]
	v_pk_mul_f32 v[72:73], v[230:231], v[72:73] op_sel_hi:[0,1]
	v_pk_fma_f32 v[54:55], v[54:55], 0.5, v[70:71] op_sel_hi:[1,0,1]
	v_pk_fma_f32 v[52:53], v[52:53], 0.5, v[80:81] op_sel_hi:[1,0,1]
	v_mul_f32_e32 v76, v63, v63
	v_pk_fma_f32 v[70:71], v[50:51], 0.5, v[72:73] op_sel_hi:[1,0,1]
	v_pk_fma_f32 v[72:73], v[48:49], 0.5, v[82:83] op_sel_hi:[1,0,1]
	v_mul_f32_e32 v48, v53, v53
	v_mul_f32_e32 v49, v55, v55
	v_mul_f32_e32 v77, v69, v69
	v_fmac_f32_e32 v76, v62, v62
	v_mul_f32_e32 v50, v73, v73
	v_fmac_f32_e32 v48, v52, v52
	v_fmac_f32_e32 v49, v54, v54
	v_mul_f32_e32 v84, v67, v67
	v_fmac_f32_e32 v77, v68, v68
	v_mul_f32_e32 v51, v71, v71
	v_add_f32_e32 v59, v59, v76
	v_fmac_f32_e32 v50, v72, v72
	v_add_f32_e32 v48, v48, v49
	v_fmac_f32_e32 v84, v66, v66
	v_add_f32_e32 v59, v77, v59
	v_add_f32_e32 v48, v50, v48
	v_fmac_f32_e32 v51, v70, v70
	v_add_f32_e32 v49, v84, v59
	v_add_f32_e32 v48, v51, v48
	v_add_f32_e32 v48, v49, v48
	ds_bpermute_b32 v49, v160, v48
	v_cvt_pk_bf16_f32 v59, v66, v67
	v_cvt_pk_bf16_f32 v50, v52, v53
	v_cvt_pk_bf16_f32 v51, v54, v55
	v_cvt_pk_bf16_f32 v52, v72, v73
	s_waitcnt lgkmcnt(0)
	v_add_f32_e32 v48, v48, v49
	ds_bpermute_b32 v49, v159, v48
	v_cvt_pk_bf16_f32 v53, v70, v71
	v_lshl_add_u64 v[54:55], s[34:35], 0, v[74:75]
	global_store_dwordx4 v[78:79], v[56:59], off
	global_store_dwordx4 v[54:55], v[50:53], off
	s_and_saveexec_b64 s[12:13], s[2:3]
	s_cbranch_execz .LBB0_555
	v_lshl_add_u64 v[50:51], v[64:65], 2, s[42:43]
	s_waitcnt lgkmcnt(0)
	v_add_f32_e32 v48, v48, v49
	global_atomic_add_f32 v[50:51], v48, off
.LBB0_555:
	s_or_b64 exec, exec, s[12:13]
	v_add_u32_e32 v48, 0x90, v150
	s_waitcnt lgkmcnt(0)
	v_ashrrev_i32_e32 v49, 31, v48
	v_lshlrev_b64 v[50:51], 10, v[48:49]
	v_lshl_add_u64 v[50:51], v[50:51], 0, v[148:149]
	v_lshlrev_b64 v[58:59], 1, v[50:51]
	v_lshl_add_u64 v[50:51], s[14:15], 0, v[58:59]
	v_lshl_add_u64 v[62:63], s[34:35], 0, v[58:59]
	v_or_b32_e32 v58, 0x100, v58
	v_lshl_add_u64 v[54:55], s[14:15], 0, v[58:59]
	s_nop 0
	s_nop 0
	s_nop 0
	v_lshlrev_b32_e32 v64, 16, v206
	s_nop 0
	v_and_b32_e32 v65, 0xffff0000, v206
	v_lshlrev_b32_e32 v50, 16, v207
	v_and_b32_e32 v51, 0xffff0000, v207
	v_lshlrev_b32_e32 v66, 16, v208
	v_and_b32_e32 v67, 0xffff0000, v208
	v_lshlrev_b32_e32 v52, 16, v209
	v_and_b32_e32 v53, 0xffff0000, v209
	v_pk_mul_f32 v[64:65], v[232:233], v[64:65] op_sel_hi:[0,1]
	v_pk_mul_f32 v[50:51], v[232:233], v[50:51] op_sel_hi:[0,1]
	v_pk_mul_f32 v[66:67], v[232:233], v[66:67] op_sel_hi:[0,1]
	v_pk_mul_f32 v[52:53], v[232:233], v[52:53] op_sel_hi:[0,1]
	v_pk_fma_f32 v[44:45], v[44:45], 0.5, v[64:65] op_sel_hi:[1,0,1]
	v_pk_fma_f32 v[46:47], v[46:47], 0.5, v[50:51] op_sel_hi:[1,0,1]
	v_pk_fma_f32 v[50:51], v[42:43], 0.5, v[52:53] op_sel_hi:[1,0,1]
	v_pk_fma_f32 v[52:53], v[40:41], 0.5, v[66:67] op_sel_hi:[1,0,1]
	v_mul_f32_e32 v43, v45, v45
	v_fmac_f32_e32 v43, v44, v44
	v_cvt_pk_bf16_f32 v40, v44, v45
	v_cvt_pk_bf16_f32 v41, v46, v47
	v_cvt_pk_bf16_f32 v42, v52, v53
	v_lshlrev_b32_e32 v68, 16, v210
	v_and_b32_e32 v69, 0xffff0000, v210
	v_lshlrev_b32_e32 v54, 16, v211
	v_and_b32_e32 v55, 0xffff0000, v211
	v_lshlrev_b32_e32 v70, 16, v212
	v_and_b32_e32 v71, 0xffff0000, v212
	v_lshlrev_b32_e32 v56, 16, v213
	v_and_b32_e32 v57, 0xffff0000, v213
	v_pk_mul_f32 v[64:65], v[232:233], v[68:69] op_sel_hi:[0,1]
	v_pk_mul_f32 v[54:55], v[232:233], v[54:55] op_sel_hi:[0,1]
	v_pk_mul_f32 v[66:67], v[232:233], v[70:71] op_sel_hi:[0,1]
	v_pk_mul_f32 v[56:57], v[232:233], v[56:57] op_sel_hi:[0,1]
	v_pk_fma_f32 v[38:39], v[38:39], 0.5, v[54:55] op_sel_hi:[1,0,1]
	v_pk_fma_f32 v[36:37], v[36:37], 0.5, v[64:65] op_sel_hi:[1,0,1]
	v_mul_f32_e32 v60, v47, v47
	v_pk_fma_f32 v[54:55], v[34:35], 0.5, v[56:57] op_sel_hi:[1,0,1]
	v_pk_fma_f32 v[56:57], v[32:33], 0.5, v[66:67] op_sel_hi:[1,0,1]
	v_mul_f32_e32 v32, v37, v37
	v_mul_f32_e32 v33, v39, v39
	v_mul_f32_e32 v61, v53, v53
	v_fmac_f32_e32 v60, v46, v46
	v_mul_f32_e32 v34, v57, v57
	v_fmac_f32_e32 v32, v36, v36
	v_fmac_f32_e32 v33, v38, v38
	v_mul_f32_e32 v68, v51, v51
	v_fmac_f32_e32 v61, v52, v52
	v_mul_f32_e32 v35, v55, v55
	v_add_f32_e32 v43, v43, v60
	v_fmac_f32_e32 v34, v56, v56
	v_add_f32_e32 v32, v32, v33
	v_fmac_f32_e32 v68, v50, v50
	v_add_f32_e32 v43, v61, v43
	v_add_f32_e32 v32, v34, v32
	v_fmac_f32_e32 v35, v54, v54
	v_add_f32_e32 v33, v68, v43
	v_add_f32_e32 v32, v35, v32
	v_add_f32_e32 v32, v33, v32
	ds_bpermute_b32 v33, v160, v32
	v_cvt_pk_bf16_f32 v43, v50, v51
	v_cvt_pk_bf16_f32 v34, v36, v37
	v_cvt_pk_bf16_f32 v35, v38, v39
	v_cvt_pk_bf16_f32 v36, v56, v57
	s_waitcnt lgkmcnt(0)
	v_add_f32_e32 v32, v32, v33
	ds_bpermute_b32 v33, v159, v32
	v_cvt_pk_bf16_f32 v37, v54, v55
	v_lshl_add_u64 v[38:39], s[34:35], 0, v[58:59]
	global_store_dwordx4 v[62:63], v[40:43], off
	global_store_dwordx4 v[38:39], v[34:37], off
	s_and_saveexec_b64 s[12:13], s[2:3]
	s_cbranch_execz .LBB0_557
	v_lshl_add_u64 v[34:35], v[48:49], 2, s[42:43]
	s_waitcnt lgkmcnt(0)
	v_add_f32_e32 v32, v32, v33
	global_atomic_add_f32 v[34:35], v32, off
; DI unsigned pk2(float lo, float hi) { typedef float v2f __attribute__((ext_vector_type(2))); typedef __bf16 v2b __attribute__((ext_vector_type(2))); v2f v = {lo, hi}; v2b b = __builtin_convertvector(v, v2b); return __builtin_bit_cast(unsigned, b); }
; DI float bflo(unsigned w) { return __uint_as_float(w << 16); }
; DI float bfhi(unsigned w) { return __uint_as_float(w & 0xffff0000u); }
; DI void atomic_addf(float* p, float v) { __builtin_amdgcn_global_atomic_fadd_f32((__attribute__((address_space(1))) float*)p, v); }
; DI float quad_sum(float s) { s += __shfl_xor(s, 16); s += __shfl_xor(s, 32); return s; }
;     DI void operator()(const f32x4 (&acc)[2][2][4][2], const Unit& u, int wr, int wc, int fr, int fq) const {
;         const int row0 = u.pm * 256 + wr * 64 + fr, col0 = u.pn * 256 + wc * 32 + 8 * fq;
; #pragma unroll
;         for (int ai = 0; ai < 2; ++ai)
; #pragma unroll
;             for (int m = 0; m < 4; ++m) {
;                 const int row = row0 + ai * 128 + m * 16; float ss = 0.f;
;                 const float bs = (B16 && base) ? base[row] : 1.0f;
; #pragma unroll
;                 for (int bj = 0; bj < 2; ++bj) {
;                     const size_t off = (size_t)row * DM + col0 + bj * 128;
;                     f32x4 b0, b1;
;                     if (B16) { const u32x4 bb = *(const u32x4*)(base16 + off); b0 = (f32x4){bflo(bb.x), bfhi(bb.x), bflo(bb.y), bfhi(bb.y)}; b1 = (f32x4){bflo(bb.z), bfhi(bb.z), bflo(bb.w), bfhi(bb.w)}; b0 = b0 * bs; b1 = b1 * bs; }
;                     else { b0 = *(const f32x4*)(base + off); b1 = *(const f32x4*)(base + off + 4); }
;                     const f32x4 o0 = b0 + acc[ai][bj][m][0] * alpha, o1 = b1 + acc[ai][bj][m][1] * alpha;
;                     if (WOUT) { *(f32x4*)(out + off) = o0; *(f32x4*)(out + off + 4) = o1; }
;                     if (WB) { ss += (o0[0] * o0[0] + o0[1] * o0[1]) + (o0[2] * o0[2] + o0[3] * o0[3]) + (o1[0] * o1[0] + o1[1] * o1[1]) + (o1[2] * o1[2] + o1[3] * o1[3]);
;                         u32x4 w; w.x = pk2(o0[0], o0[1]); w.y = pk2(o0[2], o0[3]); w.z = pk2(o1[0], o1[1]); w.w = pk2(o1[2], o1[3]); *(u32x4*)(xb + off) = w; }
;                 }
;                 if (WB) { ss = quad_sum(ss); if (fq == 0) atomic_addf(P + row, ss); }
;             }
.LBB0_557:
	s_or_b64 exec, exec, s[12:13]
	v_add_u32_e32 v32, 0xa0, v150
	s_waitcnt lgkmcnt(0)
	v_ashrrev_i32_e32 v33, 31, v32
	v_lshlrev_b64 v[34:35], 10, v[32:33]
	v_lshl_add_u64 v[34:35], v[34:35], 0, v[148:149]
	v_lshlrev_b64 v[42:43], 1, v[34:35]
	v_lshl_add_u64 v[34:35], s[14:15], 0, v[42:43]
	v_lshl_add_u64 v[46:47], s[34:35], 0, v[42:43]
	v_or_b32_e32 v42, 0x100, v42
	v_lshl_add_u64 v[38:39], s[14:15], 0, v[42:43]
	s_nop 0
	s_nop 0
	s_nop 0
	v_lshlrev_b32_e32 v48, 16, v214
	s_nop 0
	v_and_b32_e32 v49, 0xffff0000, v214
	v_lshlrev_b32_e32 v34, 16, v215
	v_and_b32_e32 v35, 0xffff0000, v215
	v_lshlrev_b32_e32 v50, 16, v216
	v_and_b32_e32 v51, 0xffff0000, v216
	v_lshlrev_b32_e32 v36, 16, v217
	v_and_b32_e32 v37, 0xffff0000, v217
	v_pk_mul_f32 v[48:49], v[234:235], v[48:49] op_sel_hi:[0,1]
	v_pk_mul_f32 v[34:35], v[234:235], v[34:35] op_sel_hi:[0,1]
	v_pk_mul_f32 v[50:51], v[234:235], v[50:51] op_sel_hi:[0,1]
	v_pk_mul_f32 v[36:37], v[234:235], v[36:37] op_sel_hi:[0,1]
	v_pk_fma_f32 v[28:29], v[28:29], 0.5, v[48:49] op_sel_hi:[1,0,1]
	v_pk_fma_f32 v[30:31], v[30:31], 0.5, v[34:35] op_sel_hi:[1,0,1]
	v_pk_fma_f32 v[34:35], v[26:27], 0.5, v[36:37] op_sel_hi:[1,0,1]
	v_pk_fma_f32 v[36:37], v[24:25], 0.5, v[50:51] op_sel_hi:[1,0,1]
	v_mul_f32_e32 v27, v29, v29
	v_fmac_f32_e32 v27, v28, v28
	v_cvt_pk_bf16_f32 v24, v28, v29
	v_cvt_pk_bf16_f32 v25, v30, v31
	v_cvt_pk_bf16_f32 v26, v36, v37
	v_lshlrev_b32_e32 v52, 16, v218
	v_and_b32_e32 v53, 0xffff0000, v218
	v_lshlrev_b32_e32 v38, 16, v219
	v_and_b32_e32 v39, 0xffff0000, v219
	v_lshlrev_b32_e32 v54, 16, v220
	v_and_b32_e32 v55, 0xffff0000, v220
	v_lshlrev_b32_e32 v40, 16, v221
	v_and_b32_e32 v41, 0xffff0000, v221
	v_pk_mul_f32 v[48:49], v[234:235], v[52:53] op_sel_hi:[0,1]
	v_pk_mul_f32 v[38:39], v[234:235], v[38:39] op_sel_hi:[0,1]
	v_pk_mul_f32 v[50:51], v[234:235], v[54:55] op_sel_hi:[0,1]
	v_pk_mul_f32 v[40:41], v[234:235], v[40:41] op_sel_hi:[0,1]
	v_pk_fma_f32 v[22:23], v[22:23], 0.5, v[38:39] op_sel_hi:[1,0,1]
	v_pk_fma_f32 v[20:21], v[20:21], 0.5, v[48:49] op_sel_hi:[1,0,1]
	v_mul_f32_e32 v44, v31, v31
	v_pk_fma_f32 v[38:39], v[18:19], 0.5, v[40:41] op_sel_hi:[1,0,1]
	v_pk_fma_f32 v[40:41], v[16:17], 0.5, v[50:51] op_sel_hi:[1,0,1]
	v_mul_f32_e32 v16, v21, v21
	v_mul_f32_e32 v17, v23, v23
	v_mul_f32_e32 v45, v37, v37
	v_fmac_f32_e32 v44, v30, v30
	v_mul_f32_e32 v18, v41, v41
	v_fmac_f32_e32 v16, v20, v20
	v_fmac_f32_e32 v17, v22, v22
	v_mul_f32_e32 v52, v35, v35
	v_fmac_f32_e32 v45, v36, v36
	v_mul_f32_e32 v19, v39, v39
	v_add_f32_e32 v27, v27, v44
	v_fmac_f32_e32 v18, v40, v40
	v_add_f32_e32 v16, v16, v17
	v_fmac_f32_e32 v52, v34, v34
	v_add_f32_e32 v27, v45, v27
	v_add_f32_e32 v16, v18, v16
	v_fmac_f32_e32 v19, v38, v38
	v_add_f32_e32 v17, v52, v27
	v_add_f32_e32 v16, v19, v16
	v_add_f32_e32 v16, v17, v16
	ds_bpermute_b32 v17, v160, v16
	v_cvt_pk_bf16_f32 v27, v34, v35
	v_cvt_pk_bf16_f32 v18, v20, v21
	v_cvt_pk_bf16_f32 v19, v22, v23
	v_cvt_pk_bf16_f32 v20, v40, v41
	s_waitcnt lgkmcnt(0)
	v_add_f32_e32 v16, v16, v17
	ds_bpermute_b32 v17, v159, v16
	v_cvt_pk_bf16_f32 v21, v38, v39
	v_lshl_add_u64 v[22:23], s[34:35], 0, v[42:43]
	global_store_dwordx4 v[46:47], v[24:27], off
	global_store_dwordx4 v[22:23], v[18:21], off
	s_and_saveexec_b64 s[12:13], s[2:3]
	s_cbranch_execz .LBB0_559
	v_lshl_add_u64 v[18:19], v[32:33], 2, s[42:43]
	s_waitcnt lgkmcnt(0)
	v_add_f32_e32 v16, v16, v17
	global_atomic_add_f32 v[18:19], v16, off
.LBB0_559:
	s_or_b64 exec, exec, s[12:13]
	v_add_u32_e32 v16, 0xb0, v150
	s_waitcnt lgkmcnt(0)
	v_ashrrev_i32_e32 v17, 31, v16
	v_lshlrev_b64 v[18:19], 10, v[16:17]
	v_lshl_add_u64 v[18:19], v[18:19], 0, v[148:149]
	v_lshlrev_b64 v[26:27], 1, v[18:19]
	v_lshl_add_u64 v[18:19], s[14:15], 0, v[26:27]
	v_lshl_add_u64 v[30:31], s[34:35], 0, v[26:27]
	v_or_b32_e32 v26, 0x100, v26
	v_lshl_add_u64 v[22:23], s[14:15], 0, v[26:27]
	s_nop 0
	s_nop 0
	s_nop 0
	v_lshlrev_b32_e32 v32, 16, v222
	s_nop 0
	v_and_b32_e32 v33, 0xffff0000, v222
	v_lshlrev_b32_e32 v18, 16, v223
	v_and_b32_e32 v19, 0xffff0000, v223
	v_lshlrev_b32_e32 v34, 16, v224
	v_and_b32_e32 v35, 0xffff0000, v224
	v_lshlrev_b32_e32 v20, 16, v225
	v_and_b32_e32 v21, 0xffff0000, v225
	v_pk_mul_f32 v[32:33], v[236:237], v[32:33] op_sel_hi:[0,1]
	v_pk_mul_f32 v[18:19], v[236:237], v[18:19] op_sel_hi:[0,1]
	v_pk_mul_f32 v[34:35], v[236:237], v[34:35] op_sel_hi:[0,1]
	v_pk_mul_f32 v[20:21], v[236:237], v[20:21] op_sel_hi:[0,1]
	v_pk_fma_f32 v[12:13], v[12:13], 0.5, v[32:33] op_sel_hi:[1,0,1]
	v_pk_fma_f32 v[14:15], v[14:15], 0.5, v[18:19] op_sel_hi:[1,0,1]
	v_pk_fma_f32 v[18:19], v[10:11], 0.5, v[20:21] op_sel_hi:[1,0,1]
	v_pk_fma_f32 v[20:21], v[8:9], 0.5, v[34:35] op_sel_hi:[1,0,1]
	v_mul_f32_e32 v11, v13, v13
	v_fmac_f32_e32 v11, v12, v12
	v_cvt_pk_bf16_f32 v8, v12, v13
	v_cvt_pk_bf16_f32 v9, v14, v15
	v_cvt_pk_bf16_f32 v10, v20, v21
	v_lshlrev_b32_e32 v36, 16, v226
	v_and_b32_e32 v37, 0xffff0000, v226
	v_lshlrev_b32_e32 v22, 16, v227
	v_and_b32_e32 v23, 0xffff0000, v227
	v_lshlrev_b32_e32 v38, 16, v228
	v_and_b32_e32 v39, 0xffff0000, v228
	v_lshlrev_b32_e32 v24, 16, v229
	v_and_b32_e32 v25, 0xffff0000, v229
	v_pk_mul_f32 v[32:33], v[236:237], v[36:37] op_sel_hi:[0,1]
	v_pk_mul_f32 v[22:23], v[236:237], v[22:23] op_sel_hi:[0,1]
	v_pk_mul_f32 v[34:35], v[236:237], v[38:39] op_sel_hi:[0,1]
	v_pk_mul_f32 v[24:25], v[236:237], v[24:25] op_sel_hi:[0,1]
	v_pk_fma_f32 v[6:7], v[6:7], 0.5, v[22:23] op_sel_hi:[1,0,1]
	v_pk_fma_f32 v[4:5], v[4:5], 0.5, v[32:33] op_sel_hi:[1,0,1]
	v_mul_f32_e32 v28, v15, v15
	v_pk_fma_f32 v[22:23], v[2:3], 0.5, v[24:25] op_sel_hi:[1,0,1]
	v_pk_fma_f32 v[24:25], v[0:1], 0.5, v[34:35] op_sel_hi:[1,0,1]
	v_mul_f32_e32 v0, v5, v5
	v_mul_f32_e32 v1, v7, v7
	v_mul_f32_e32 v29, v21, v21
	v_fmac_f32_e32 v28, v14, v14
	v_mul_f32_e32 v2, v25, v25
	v_fmac_f32_e32 v0, v4, v4
	v_fmac_f32_e32 v1, v6, v6
	v_mul_f32_e32 v36, v19, v19
	v_fmac_f32_e32 v29, v20, v20
	v_mul_f32_e32 v3, v23, v23
	v_add_f32_e32 v11, v11, v28
	v_fmac_f32_e32 v2, v24, v24
	v_add_f32_e32 v0, v0, v1
	v_fmac_f32_e32 v36, v18, v18
	v_add_f32_e32 v11, v29, v11
	v_add_f32_e32 v0, v2, v0
	v_fmac_f32_e32 v3, v22, v22
	v_add_f32_e32 v1, v36, v11
	v_add_f32_e32 v0, v3, v0
	v_add_f32_e32 v0, v1, v0
	ds_bpermute_b32 v1, v160, v0
	v_cvt_pk_bf16_f32 v11, v18, v19
	v_cvt_pk_bf16_f32 v2, v4, v5
	v_cvt_pk_bf16_f32 v3, v6, v7
	v_cvt_pk_bf16_f32 v4, v24, v25
	s_waitcnt lgkmcnt(0)
	v_add_f32_e32 v0, v0, v1
	ds_bpermute_b32 v1, v159, v0
	v_cvt_pk_bf16_f32 v5, v22, v23
	v_lshl_add_u64 v[6:7], s[34:35], 0, v[26:27]
	global_store_dwordx4 v[30:31], v[8:11], off
	global_store_dwordx4 v[6:7], v[2:5], off
	s_and_saveexec_b64 s[12:13], s[2:3]
	s_cbranch_execz .LBB0_561
	v_lshl_add_u64 v[2:3], v[16:17], 2, s[42:43]
	s_waitcnt lgkmcnt(0)
	v_add_f32_e32 v0, v0, v1
	global_atomic_add_f32 v[2:3], v0, off

; DI unsigned pk2(float lo, float hi) { typedef float v2f __attribute__((ext_vector_type(2))); typedef __bf16 v2b __attribute__((ext_vector_type(2))); v2f v = {lo, hi}; v2b b = __builtin_convertvector(v, v2b); return __builtin_bit_cast(unsigned, b); }
; DI float bflo(unsigned w) { return __uint_as_float(w << 16); }
; DI float bfhi(unsigned w) { return __uint_as_float(w & 0xffff0000u); }
; DI void atomic_addf(float* p, float v) { __builtin_amdgcn_global_atomic_fadd_f32((__attribute__((address_space(1))) float*)p, v); }
; DI float quad_sum(float s) { s += __shfl_xor(s, 16); s += __shfl_xor(s, 32); return s; }
;     DI void operator()(const f32x4 (&acc)[2][2][4][2], const Unit& u, int wr, int wc, int fr, int fq) const {
;         const int row0 = u.pm * 256 + wr * 64 + fr, col0 = u.pn * 256 + wc * 32 + 8 * fq;
; #pragma unroll
;         for (int ai = 0; ai < 2; ++ai)
; #pragma unroll
;             for (int m = 0; m < 4; ++m) {
;                 const int row = row0 + ai * 128 + m * 16; float ss = 0.f;
;                 const float bs = (B16 && base) ? base[row] : 1.0f;
; #pragma unroll
;                 for (int bj = 0; bj < 2; ++bj) {
;                     const size_t off = (size_t)row * DM + col0 + bj * 128;
;                     f32x4 b0, b1;
;                     if (B16) { const u32x4 bb = *(const u32x4*)(base16 + off); b0 = (f32x4){bflo(bb.x), bfhi(bb.x), bflo(bb.y), bfhi(bb.y)}; b1 = (f32x4){bflo(bb.z), bfhi(bb.z), bflo(bb.w), bfhi(bb.w)}; b0 = b0 * bs; b1 = b1 * bs; }
;                     else { b0 = *(const f32x4*)(base + off); b1 = *(const f32x4*)(base + off + 4); }
;                     const f32x4 o0 = b0 + acc[ai][bj][m][0] * alpha, o1 = b1 + acc[ai][bj][m][1] * alpha;
;                     if (WOUT) { *(f32x4*)(out + off) = o0; *(f32x4*)(out + off + 4) = o1; }
;                     if (WB) { ss += (o0[0] * o0[0] + o0[1] * o0[1]) + (o0[2] * o0[2] + o0[3] * o0[3]) + (o1[0] * o1[0] + o1[1] * o1[1]) + (o1[2] * o1[2] + o1[3] * o1[3]);
;                         u32x4 w; w.x = pk2(o0[0], o0[1]); w.y = pk2(o0[2], o0[3]); w.z = pk2(o1[0], o1[1]); w.w = pk2(o1[2], o1[3]); *(u32x4*)(xb + off) = w; }
;                 }
;                 if (WB) { ss = quad_sum(ss); if (fq == 0) atomic_addf(P + row, ss); }
;             }
.LBB0_1739:
	v_lshl_add_u32 v146, s36, 8, v148
	v_lshl_or_b32 v144, s34, 8, v150
	v_ashrrev_i32_e32 v147, 31, v146
	v_ashrrev_i32_e32 v145, 31, v144
	v_lshlrev_b64 v[156:157], 10, v[146:147]
	v_lshl_add_u64 v[156:157], v[156:157], 0, v[144:145]
	v_lshlrev_b64 v[166:167], 1, v[156:157]
	v_lshl_add_u64 v[156:157], s[8:9], 0, v[166:167]
	v_lshl_add_u64 v[168:169], s[10:11], 0, v[166:167]
	v_mov_b32_e32 v190, v166
	v_mov_b32_e32 v191, v167
	v_mov_b32_e32 v184, v190
	v_mov_b32_e32 v185, v191
	v_lshl_add_u64 v[186:187], s[8:9], 0, v[184:185]
	global_load_dwordx4 v[198:201], v[186:187], off
	global_load_dwordx4 v[202:205], v[186:187], off offset:256
	v_add_u32_e32 v184, 0x8000, v190
	v_mov_b32_e32 v185, v191
	v_lshl_add_u64 v[186:187], s[8:9], 0, v[184:185]
	global_load_dwordx4 v[206:209], v[186:187], off
	global_load_dwordx4 v[210:213], v[186:187], off offset:256
	v_add_u32_e32 v184, 0x10000, v190
	v_mov_b32_e32 v185, v191
	v_lshl_add_u64 v[186:187], s[8:9], 0, v[184:185]
	global_load_dwordx4 v[214:217], v[186:187], off
	global_load_dwordx4 v[218:221], v[186:187], off offset:256
	v_add_u32_e32 v184, 0x18000, v190
	v_mov_b32_e32 v185, v191
	v_lshl_add_u64 v[186:187], s[8:9], 0, v[184:185]
	global_load_dwordx4 v[222:225], v[186:187], off
	global_load_dwordx4 v[226:229], v[186:187], off offset:256
	v_or_b32_e32 v166, 0x100, v166
	s_nop 0
	v_lshl_add_u64 v[156:157], s[8:9], 0, v[166:167]
	s_nop 0
	v_and_b32_e32 v156, 64, v154
	v_xor_b32_e32 v155, 16, v154
	v_add_u32_e32 v156, 64, v156
	v_xor_b32_e32 v157, 32, v154
	v_cmp_lt_i32_e32 vcc, v155, v156
	s_waitcnt vmcnt(0)
	v_lshlrev_b32_e32 v170, 16, v198
	v_and_b32_e32 v171, 0xffff0000, v198
	v_cndmask_b32_e32 v155, v154, v155, vcc
	v_cmp_lt_i32_e32 vcc, v157, v156
	v_lshlrev_b32_e32 v158, 16, v199
	v_and_b32_e32 v159, 0xffff0000, v199
	v_lshlrev_b32_e32 v172, 16, v200
	v_and_b32_e32 v173, 0xffff0000, v200
	v_lshlrev_b32_e32 v160, 16, v201
	v_and_b32_e32 v161, 0xffff0000, v201
	v_pk_add_f32 v[124:125], v[124:125], v[170:171]
	v_lshlrev_b32_e32 v170, 16, v202
	v_and_b32_e32 v171, 0xffff0000, v202
	v_lshlrev_b32_e32 v162, 16, v203
	v_and_b32_e32 v163, 0xffff0000, v203
	v_cndmask_b32_e32 v157, v154, v157, vcc
	v_pk_add_f32 v[126:127], v[126:127], v[158:159]
	v_pk_add_f32 v[158:159], v[122:123], v[160:161]
	v_pk_add_f32 v[160:161], v[120:121], v[172:173]
	v_lshlrev_b32_e32 v172, 16, v204
	v_and_b32_e32 v173, 0xffff0000, v204
	v_lshlrev_b32_e32 v164, 16, v205
	v_and_b32_e32 v165, 0xffff0000, v205
	v_pk_add_f32 v[118:119], v[118:119], v[162:163]
	v_pk_add_f32 v[116:117], v[116:117], v[170:171]
	v_lshlrev_b32_e32 v156, 2, v155
	v_lshlrev_b32_e32 v155, 2, v157
	v_mul_f32_e32 v123, v125, v125
	v_mul_f32_e32 v157, v127, v127
	v_pk_add_f32 v[162:163], v[114:115], v[164:165]
	v_pk_add_f32 v[164:165], v[112:113], v[172:173]
	v_mul_f32_e32 v112, v117, v117
	v_mul_f32_e32 v113, v119, v119
	v_mul_f32_e32 v174, v161, v161
	v_fmac_f32_e32 v123, v124, v124
	v_fmac_f32_e32 v157, v126, v126
	v_mul_f32_e32 v114, v165, v165
	v_fmac_f32_e32 v112, v116, v116
	v_fmac_f32_e32 v113, v118, v118
	v_mul_f32_e32 v175, v159, v159
	v_fmac_f32_e32 v174, v160, v160
	v_mul_f32_e32 v115, v163, v163
	v_add_f32_e32 v123, v123, v157
	v_fmac_f32_e32 v114, v164, v164
	v_add_f32_e32 v112, v112, v113
	v_fmac_f32_e32 v175, v158, v158
	v_add_f32_e32 v123, v174, v123
	v_add_f32_e32 v112, v114, v112
	v_fmac_f32_e32 v115, v162, v162
	v_add_f32_e32 v113, v175, v123
	v_add_f32_e32 v112, v115, v112
	v_add_f32_e32 v112, v113, v112
	ds_bpermute_b32 v113, v156, v112
	v_cvt_pk_bf16_f32 v120, v124, v125
	v_cvt_pk_bf16_f32 v121, v126, v127
	v_cvt_pk_bf16_f32 v122, v160, v161
	v_cvt_pk_bf16_f32 v123, v158, v159
	s_waitcnt lgkmcnt(0)
	v_add_f32_e32 v112, v112, v113
	ds_bpermute_b32 v113, v155, v112
	v_cvt_pk_bf16_f32 v114, v116, v117
	v_cvt_pk_bf16_f32 v115, v118, v119
	v_cvt_pk_bf16_f32 v116, v164, v165
	v_cvt_pk_bf16_f32 v117, v162, v163
	v_lshl_add_u64 v[118:119], s[10:11], 0, v[166:167]
	global_store_dwordx4 v[168:169], v[120:123], off
	global_store_dwordx4 v[118:119], v[114:117], off
	s_and_saveexec_b64 s[12:13], s[2:3]
	s_cbranch_execz .LBB0_1741
	v_lshl_add_u64 v[114:115], v[146:147], 2, s[14:15]
	s_waitcnt lgkmcnt(0)
	v_add_f32_e32 v112, v112, v113
	global_atomic_add_f32 v[114:115], v112, off
; DI unsigned pk2(float lo, float hi) { typedef float v2f __attribute__((ext_vector_type(2))); typedef __bf16 v2b __attribute__((ext_vector_type(2))); v2f v = {lo, hi}; v2b b = __builtin_convertvector(v, v2b); return __builtin_bit_cast(unsigned, b); }
; DI float bflo(unsigned w) { return __uint_as_float(w << 16); }
; DI float bfhi(unsigned w) { return __uint_as_float(w & 0xffff0000u); }
; DI void atomic_addf(float* p, float v) { __builtin_amdgcn_global_atomic_fadd_f32((__attribute__((address_space(1))) float*)p, v); }
; DI float quad_sum(float s) { s += __shfl_xor(s, 16); s += __shfl_xor(s, 32); return s; }
;     DI void operator()(const f32x4 (&acc)[2][2][4][2], const Unit& u, int wr, int wc, int fr, int fq) const {
;         const int row0 = u.pm * 256 + wr * 64 + fr, col0 = u.pn * 256 + wc * 32 + 8 * fq;
; #pragma unroll
;         for (int ai = 0; ai < 2; ++ai)
; #pragma unroll
;             for (int m = 0; m < 4; ++m) {
;                 const int row = row0 + ai * 128 + m * 16; float ss = 0.f;
;                 const float bs = (B16 && base) ? base[row] : 1.0f;
; #pragma unroll
;                 for (int bj = 0; bj < 2; ++bj) {
;                     const size_t off = (size_t)row * DM + col0 + bj * 128;
;                     f32x4 b0, b1;
;                     if (B16) { const u32x4 bb = *(const u32x4*)(base16 + off); b0 = (f32x4){bflo(bb.x), bfhi(bb.x), bflo(bb.y), bfhi(bb.y)}; b1 = (f32x4){bflo(bb.z), bfhi(bb.z), bflo(bb.w), bfhi(bb.w)}; b0 = b0 * bs; b1 = b1 * bs; }
;                     else { b0 = *(const f32x4*)(base + off); b1 = *(const f32x4*)(base + off + 4); }
;                     const f32x4 o0 = b0 + acc[ai][bj][m][0] * alpha, o1 = b1 + acc[ai][bj][m][1] * alpha;
;                     if (WOUT) { *(f32x4*)(out + off) = o0; *(f32x4*)(out + off + 4) = o1; }
;                     if (WB) { ss += (o0[0] * o0[0] + o0[1] * o0[1]) + (o0[2] * o0[2] + o0[3] * o0[3]) + (o1[0] * o1[0] + o1[1] * o1[1]) + (o1[2] * o1[2] + o1[3] * o1[3]);
;                         u32x4 w; w.x = pk2(o0[0], o0[1]); w.y = pk2(o0[2], o0[3]); w.z = pk2(o1[0], o1[1]); w.w = pk2(o1[2], o1[3]); *(u32x4*)(xb + off) = w; }
;                 }
;                 if (WB) { ss = quad_sum(ss); if (fq == 0) atomic_addf(P + row, ss); }
;             }
.LBB0_1741:
	s_or_b64 exec, exec, s[12:13]
	v_or_b32_e32 v112, 16, v146
	s_waitcnt lgkmcnt(0)
	v_ashrrev_i32_e32 v113, 31, v112
	v_lshlrev_b64 v[114:115], 10, v[112:113]
	v_lshl_add_u64 v[114:115], v[114:115], 0, v[144:145]
	v_lshlrev_b64 v[122:123], 1, v[114:115]
	v_lshl_add_u64 v[114:115], s[8:9], 0, v[122:123]
	v_lshl_add_u64 v[124:125], s[10:11], 0, v[122:123]
	v_or_b32_e32 v122, 0x100, v122
	s_nop 0
	v_lshl_add_u64 v[118:119], s[8:9], 0, v[122:123]
	s_nop 0
	v_lshlrev_b32_e32 v126, 16, v206
	v_and_b32_e32 v127, 0xffff0000, v206
	v_lshlrev_b32_e32 v114, 16, v207
	v_and_b32_e32 v115, 0xffff0000, v207
	v_lshlrev_b32_e32 v158, 16, v208
	v_and_b32_e32 v159, 0xffff0000, v208
	v_lshlrev_b32_e32 v116, 16, v209
	v_and_b32_e32 v117, 0xffff0000, v209
	v_pk_add_f32 v[108:109], v[108:109], v[126:127]
	v_lshlrev_b32_e32 v126, 16, v210
	v_and_b32_e32 v127, 0xffff0000, v210
	v_lshlrev_b32_e32 v118, 16, v211
	v_and_b32_e32 v119, 0xffff0000, v211
	v_pk_add_f32 v[110:111], v[110:111], v[114:115]
	v_pk_add_f32 v[114:115], v[106:107], v[116:117]
	v_pk_add_f32 v[116:117], v[104:105], v[158:159]
	v_lshlrev_b32_e32 v158, 16, v212
	v_and_b32_e32 v159, 0xffff0000, v212
	v_lshlrev_b32_e32 v120, 16, v213
	v_and_b32_e32 v121, 0xffff0000, v213
	v_pk_add_f32 v[102:103], v[102:103], v[118:119]
	v_pk_add_f32 v[100:101], v[100:101], v[126:127]
	v_mul_f32_e32 v107, v109, v109
	v_mul_f32_e32 v147, v111, v111
	v_pk_add_f32 v[118:119], v[98:99], v[120:121]
	v_pk_add_f32 v[120:121], v[96:97], v[158:159]
	v_mul_f32_e32 v96, v101, v101
	v_mul_f32_e32 v97, v103, v103
	v_mul_f32_e32 v157, v117, v117
	v_fmac_f32_e32 v107, v108, v108
	v_fmac_f32_e32 v147, v110, v110
	v_mul_f32_e32 v98, v121, v121
	v_fmac_f32_e32 v96, v100, v100
	v_fmac_f32_e32 v97, v102, v102
	v_mul_f32_e32 v160, v115, v115
	v_fmac_f32_e32 v157, v116, v116
	v_mul_f32_e32 v99, v119, v119
	v_add_f32_e32 v107, v107, v147
	v_fmac_f32_e32 v98, v120, v120
	v_add_f32_e32 v96, v96, v97
	v_fmac_f32_e32 v160, v114, v114
	v_add_f32_e32 v107, v157, v107
	v_add_f32_e32 v96, v98, v96
	v_fmac_f32_e32 v99, v118, v118
	v_add_f32_e32 v97, v160, v107
	v_add_f32_e32 v96, v99, v96
	v_add_f32_e32 v96, v97, v96
	ds_bpermute_b32 v97, v156, v96
	v_cvt_pk_bf16_f32 v104, v108, v109
	v_cvt_pk_bf16_f32 v105, v110, v111
	v_cvt_pk_bf16_f32 v106, v116, v117
	v_cvt_pk_bf16_f32 v107, v114, v115
	s_waitcnt lgkmcnt(0)
	v_add_f32_e32 v96, v96, v97
	ds_bpermute_b32 v97, v155, v96
	v_cvt_pk_bf16_f32 v98, v100, v101
	v_cvt_pk_bf16_f32 v99, v102, v103
	v_cvt_pk_bf16_f32 v100, v120, v121
	v_cvt_pk_bf16_f32 v101, v118, v119
	v_lshl_add_u64 v[102:103], s[10:11], 0, v[122:123]
	global_store_dwordx4 v[124:125], v[104:107], off
	global_store_dwordx4 v[102:103], v[98:101], off
	s_and_saveexec_b64 s[12:13], s[2:3]
	s_cbranch_execz .LBB0_1743
	v_lshl_add_u64 v[98:99], v[112:113], 2, s[14:15]
	s_waitcnt lgkmcnt(0)
	v_add_f32_e32 v96, v96, v97
	global_atomic_add_f32 v[98:99], v96, off
.LBB0_1743:
	s_or_b64 exec, exec, s[12:13]
	v_or_b32_e32 v96, 32, v146
	s_waitcnt lgkmcnt(0)
	v_ashrrev_i32_e32 v97, 31, v96
	v_lshlrev_b64 v[98:99], 10, v[96:97]
	v_lshl_add_u64 v[98:99], v[98:99], 0, v[144:145]
	v_lshlrev_b64 v[106:107], 1, v[98:99]
	v_lshl_add_u64 v[98:99], s[8:9], 0, v[106:107]
	v_lshl_add_u64 v[108:109], s[10:11], 0, v[106:107]
	v_or_b32_e32 v106, 0x100, v106
	s_nop 0
	v_lshl_add_u64 v[102:103], s[8:9], 0, v[106:107]
	s_nop 0
	v_lshlrev_b32_e32 v110, 16, v214
	v_and_b32_e32 v111, 0xffff0000, v214
	v_lshlrev_b32_e32 v98, 16, v215
	v_and_b32_e32 v99, 0xffff0000, v215
	v_lshlrev_b32_e32 v112, 16, v216
	v_and_b32_e32 v113, 0xffff0000, v216
	v_lshlrev_b32_e32 v100, 16, v217
	v_and_b32_e32 v101, 0xffff0000, v217
	v_pk_add_f32 v[92:93], v[92:93], v[110:111]
	v_lshlrev_b32_e32 v110, 16, v218
	v_and_b32_e32 v111, 0xffff0000, v218
	v_lshlrev_b32_e32 v102, 16, v219
	v_and_b32_e32 v103, 0xffff0000, v219
	v_pk_add_f32 v[94:95], v[94:95], v[98:99]
	v_pk_add_f32 v[98:99], v[90:91], v[100:101]
	v_pk_add_f32 v[100:101], v[88:89], v[112:113]
	v_lshlrev_b32_e32 v112, 16, v220
	v_and_b32_e32 v113, 0xffff0000, v220
	v_lshlrev_b32_e32 v104, 16, v221
	v_and_b32_e32 v105, 0xffff0000, v221
	v_pk_add_f32 v[86:87], v[86:87], v[102:103]
	v_pk_add_f32 v[84:85], v[84:85], v[110:111]
	v_mul_f32_e32 v91, v93, v93
	v_mul_f32_e32 v114, v95, v95
	v_pk_add_f32 v[102:103], v[82:83], v[104:105]
	v_pk_add_f32 v[104:105], v[80:81], v[112:113]
	v_mul_f32_e32 v80, v85, v85
	v_mul_f32_e32 v81, v87, v87
	v_mul_f32_e32 v115, v101, v101
	v_fmac_f32_e32 v91, v92, v92
	v_fmac_f32_e32 v114, v94, v94
	v_mul_f32_e32 v82, v105, v105
	v_fmac_f32_e32 v80, v84, v84
	v_fmac_f32_e32 v81, v86, v86
	v_mul_f32_e32 v116, v99, v99
	v_fmac_f32_e32 v115, v100, v100
	v_mul_f32_e32 v83, v103, v103
	v_add_f32_e32 v91, v91, v114
	v_fmac_f32_e32 v82, v104, v104
	v_add_f32_e32 v80, v80, v81
	v_fmac_f32_e32 v116, v98, v98
	v_add_f32_e32 v91, v115, v91
	v_add_f32_e32 v80, v82, v80
	v_fmac_f32_e32 v83, v102, v102
	v_add_f32_e32 v81, v116, v91
	v_add_f32_e32 v80, v83, v80
	v_add_f32_e32 v80, v81, v80
	ds_bpermute_b32 v81, v156, v80
	v_cvt_pk_bf16_f32 v88, v92, v93
	v_cvt_pk_bf16_f32 v89, v94, v95
	v_cvt_pk_bf16_f32 v90, v100, v101
	v_cvt_pk_bf16_f32 v91, v98, v99
	s_waitcnt lgkmcnt(0)
	v_add_f32_e32 v80, v80, v81
	ds_bpermute_b32 v81, v155, v80
	v_cvt_pk_bf16_f32 v82, v84, v85
	v_cvt_pk_bf16_f32 v83, v86, v87
	v_cvt_pk_bf16_f32 v84, v104, v105
	v_cvt_pk_bf16_f32 v85, v102, v103
	v_lshl_add_u64 v[86:87], s[10:11], 0, v[106:107]
	global_store_dwordx4 v[108:109], v[88:91], off
	global_store_dwordx4 v[86:87], v[82:85], off
	s_and_saveexec_b64 s[12:13], s[2:3]
	v_readlane_b32 s56, v249, 1
	v_readlane_b32 s68, v249, 13
	v_readlane_b32 s69, v249, 14
	v_readlane_b32 s70, v249, 15
	v_readlane_b32 s71, v249, 16
	s_mov_b64 s[28:29], s[68:69]
	s_mov_b64 s[30:31], s[70:71]
	v_readlane_b32 s57, v249, 2
	v_readlane_b32 s58, v249, 3
	v_readlane_b32 s59, v249, 4
	v_readlane_b32 s60, v249, 5
	v_readlane_b32 s61, v249, 6
	v_readlane_b32 s62, v249, 7
	v_readlane_b32 s63, v249, 8
	v_readlane_b32 s64, v249, 9
	v_readlane_b32 s65, v249, 10
	v_readlane_b32 s66, v249, 11
	v_readlane_b32 s67, v249, 12
	s_cbranch_execz .LBB0_1745
	v_lshl_add_u64 v[82:83], v[96:97], 2, s[14:15]
	s_waitcnt lgkmcnt(0)
	v_add_f32_e32 v80, v80, v81
	global_atomic_add_f32 v[82:83], v80, off
; DI unsigned pk2(float lo, float hi) { typedef float v2f __attribute__((ext_vector_type(2))); typedef __bf16 v2b __attribute__((ext_vector_type(2))); v2f v = {lo, hi}; v2b b = __builtin_convertvector(v, v2b); return __builtin_bit_cast(unsigned, b); }
; DI float bflo(unsigned w) { return __uint_as_float(w << 16); }
; DI float bfhi(unsigned w) { return __uint_as_float(w & 0xffff0000u); }
; DI void atomic_addf(float* p, float v) { __builtin_amdgcn_global_atomic_fadd_f32((__attribute__((address_space(1))) float*)p, v); }
; DI float quad_sum(float s) { s += __shfl_xor(s, 16); s += __shfl_xor(s, 32); return s; }
;     DI void operator()(const f32x4 (&acc)[2][2][4][2], const Unit& u, int wr, int wc, int fr, int fq) const {
;         const int row0 = u.pm * 256 + wr * 64 + fr, col0 = u.pn * 256 + wc * 32 + 8 * fq;
; #pragma unroll
;         for (int ai = 0; ai < 2; ++ai)
; #pragma unroll
;             for (int m = 0; m < 4; ++m) {
;                 const int row = row0 + ai * 128 + m * 16; float ss = 0.f;
;                 const float bs = (B16 && base) ? base[row] : 1.0f;
; #pragma unroll
;                 for (int bj = 0; bj < 2; ++bj) {
;                     const size_t off = (size_t)row * DM + col0 + bj * 128;
;                     f32x4 b0, b1;
;                     if (B16) { const u32x4 bb = *(const u32x4*)(base16 + off); b0 = (f32x4){bflo(bb.x), bfhi(bb.x), bflo(bb.y), bfhi(bb.y)}; b1 = (f32x4){bflo(bb.z), bfhi(bb.z), bflo(bb.w), bfhi(bb.w)}; b0 = b0 * bs; b1 = b1 * bs; }
;                     else { b0 = *(const f32x4*)(base + off); b1 = *(const f32x4*)(base + off + 4); }
;                     const f32x4 o0 = b0 + acc[ai][bj][m][0] * alpha, o1 = b1 + acc[ai][bj][m][1] * alpha;
;                     if (WOUT) { *(f32x4*)(out + off) = o0; *(f32x4*)(out + off + 4) = o1; }
;                     if (WB) { ss += (o0[0] * o0[0] + o0[1] * o0[1]) + (o0[2] * o0[2] + o0[3] * o0[3]) + (o1[0] * o1[0] + o1[1] * o1[1]) + (o1[2] * o1[2] + o1[3] * o1[3]);
;                         u32x4 w; w.x = pk2(o0[0], o0[1]); w.y = pk2(o0[2], o0[3]); w.z = pk2(o1[0], o1[1]); w.w = pk2(o1[2], o1[3]); *(u32x4*)(xb + off) = w; }
;                 }
;                 if (WB) { ss = quad_sum(ss); if (fq == 0) atomic_addf(P + row, ss); }
;             }
.LBB0_1745:
	s_or_b64 exec, exec, s[12:13]
	v_or_b32_e32 v80, 48, v146
	s_waitcnt lgkmcnt(0)
	v_ashrrev_i32_e32 v81, 31, v80
	v_lshlrev_b64 v[82:83], 10, v[80:81]
	v_lshl_add_u64 v[82:83], v[82:83], 0, v[144:145]
	v_lshlrev_b64 v[90:91], 1, v[82:83]
	v_lshl_add_u64 v[82:83], s[8:9], 0, v[90:91]
	v_lshl_add_u64 v[92:93], s[10:11], 0, v[90:91]
	v_or_b32_e32 v90, 0x100, v90
	s_nop 0
	v_lshl_add_u64 v[86:87], s[8:9], 0, v[90:91]
	s_nop 0
	v_lshlrev_b32_e32 v94, 16, v222
	v_and_b32_e32 v95, 0xffff0000, v222
	v_lshlrev_b32_e32 v82, 16, v223
	v_and_b32_e32 v83, 0xffff0000, v223
	v_lshlrev_b32_e32 v96, 16, v224
	v_and_b32_e32 v97, 0xffff0000, v224
	v_lshlrev_b32_e32 v84, 16, v225
	v_and_b32_e32 v85, 0xffff0000, v225
	v_pk_add_f32 v[76:77], v[76:77], v[94:95]
	v_lshlrev_b32_e32 v94, 16, v226
	v_and_b32_e32 v95, 0xffff0000, v226
	v_lshlrev_b32_e32 v86, 16, v227
	v_and_b32_e32 v87, 0xffff0000, v227
	v_pk_add_f32 v[78:79], v[78:79], v[82:83]
	v_pk_add_f32 v[82:83], v[74:75], v[84:85]
	v_pk_add_f32 v[84:85], v[72:73], v[96:97]
	v_lshlrev_b32_e32 v96, 16, v228
	v_and_b32_e32 v97, 0xffff0000, v228
	v_lshlrev_b32_e32 v88, 16, v229
	v_and_b32_e32 v89, 0xffff0000, v229
	v_add_u32_e32 v184, 0x40000, v190
	v_mov_b32_e32 v185, v191
	v_lshl_add_u64 v[186:187], s[8:9], 0, v[184:185]
	global_load_dwordx4 v[198:201], v[186:187], off
	global_load_dwordx4 v[202:205], v[186:187], off offset:256
	v_add_u32_e32 v184, 0x48000, v190
	v_mov_b32_e32 v185, v191
	v_lshl_add_u64 v[186:187], s[8:9], 0, v[184:185]
	global_load_dwordx4 v[206:209], v[186:187], off
	global_load_dwordx4 v[210:213], v[186:187], off offset:256
	v_add_u32_e32 v184, 0x50000, v190
	v_mov_b32_e32 v185, v191
	v_lshl_add_u64 v[186:187], s[8:9], 0, v[184:185]
	global_load_dwordx4 v[214:217], v[186:187], off
	global_load_dwordx4 v[218:221], v[186:187], off offset:256
	v_add_u32_e32 v184, 0x58000, v190
	v_mov_b32_e32 v185, v191
	v_lshl_add_u64 v[186:187], s[8:9], 0, v[184:185]
	global_load_dwordx4 v[222:225], v[186:187], off
	global_load_dwordx4 v[226:229], v[186:187], off offset:256
	v_pk_add_f32 v[70:71], v[70:71], v[86:87]
	v_pk_add_f32 v[68:69], v[68:69], v[94:95]
	v_mul_f32_e32 v75, v77, v77
	v_mul_f32_e32 v98, v79, v79
	v_pk_add_f32 v[86:87], v[66:67], v[88:89]
	v_pk_add_f32 v[88:89], v[64:65], v[96:97]
	v_mul_f32_e32 v64, v69, v69
	v_mul_f32_e32 v65, v71, v71
	v_mul_f32_e32 v99, v85, v85
	v_fmac_f32_e32 v75, v76, v76
	v_fmac_f32_e32 v98, v78, v78
	v_mul_f32_e32 v66, v89, v89
	v_fmac_f32_e32 v64, v68, v68
	v_fmac_f32_e32 v65, v70, v70
	v_mul_f32_e32 v100, v83, v83
	v_fmac_f32_e32 v99, v84, v84
	v_mul_f32_e32 v67, v87, v87
	v_add_f32_e32 v75, v75, v98
	v_fmac_f32_e32 v66, v88, v88
	v_add_f32_e32 v64, v64, v65
	v_fmac_f32_e32 v100, v82, v82
	v_add_f32_e32 v75, v99, v75
	v_add_f32_e32 v64, v66, v64
	v_fmac_f32_e32 v67, v86, v86
	v_add_f32_e32 v65, v100, v75
	v_add_f32_e32 v64, v67, v64
	v_add_f32_e32 v64, v65, v64
	ds_bpermute_b32 v65, v156, v64
	v_cvt_pk_bf16_f32 v72, v76, v77
	v_cvt_pk_bf16_f32 v73, v78, v79
	v_cvt_pk_bf16_f32 v74, v84, v85
	v_cvt_pk_bf16_f32 v75, v82, v83
	s_waitcnt lgkmcnt(0)
	v_add_f32_e32 v64, v64, v65
	ds_bpermute_b32 v65, v155, v64
	v_cvt_pk_bf16_f32 v66, v68, v69
	v_cvt_pk_bf16_f32 v67, v70, v71
	v_cvt_pk_bf16_f32 v68, v88, v89
	v_cvt_pk_bf16_f32 v69, v86, v87
	v_lshl_add_u64 v[70:71], s[10:11], 0, v[90:91]
	global_store_dwordx4 v[92:93], v[72:75], off
	global_store_dwordx4 v[70:71], v[66:69], off
	s_and_saveexec_b64 s[12:13], s[2:3]
	s_cbranch_execz .LBB0_1747
	v_lshl_add_u64 v[66:67], v[80:81], 2, s[14:15]
	s_waitcnt lgkmcnt(0)
	v_add_f32_e32 v64, v64, v65
	global_atomic_add_f32 v[66:67], v64, off
.LBB0_1747:
	s_or_b64 exec, exec, s[12:13]
	v_add_u32_e32 v64, 0x80, v146
	s_waitcnt lgkmcnt(0)
	v_ashrrev_i32_e32 v65, 31, v64
	v_lshlrev_b64 v[66:67], 10, v[64:65]
	v_lshl_add_u64 v[66:67], v[66:67], 0, v[144:145]
	v_lshlrev_b64 v[74:75], 1, v[66:67]
	v_lshl_add_u64 v[66:67], s[8:9], 0, v[74:75]
	v_lshl_add_u64 v[76:77], s[10:11], 0, v[74:75]
	v_or_b32_e32 v74, 0x100, v74
	s_nop 0
	v_lshl_add_u64 v[70:71], s[8:9], 0, v[74:75]
	s_nop 0
	s_waitcnt vmcnt(2)
	v_lshlrev_b32_e32 v78, 16, v198
	v_and_b32_e32 v79, 0xffff0000, v198
	v_lshlrev_b32_e32 v66, 16, v199
	v_and_b32_e32 v67, 0xffff0000, v199
	v_lshlrev_b32_e32 v80, 16, v200
	v_and_b32_e32 v81, 0xffff0000, v200
	v_lshlrev_b32_e32 v68, 16, v201
	v_and_b32_e32 v69, 0xffff0000, v201
	v_pk_add_f32 v[60:61], v[60:61], v[78:79]
	v_lshlrev_b32_e32 v78, 16, v202
	v_and_b32_e32 v79, 0xffff0000, v202
	v_lshlrev_b32_e32 v70, 16, v203
	v_and_b32_e32 v71, 0xffff0000, v203
	v_pk_add_f32 v[62:63], v[62:63], v[66:67]
	v_pk_add_f32 v[66:67], v[58:59], v[68:69]
	v_pk_add_f32 v[68:69], v[56:57], v[80:81]
	v_lshlrev_b32_e32 v80, 16, v204
	v_and_b32_e32 v81, 0xffff0000, v204
	v_lshlrev_b32_e32 v72, 16, v205
	v_and_b32_e32 v73, 0xffff0000, v205
	v_pk_add_f32 v[54:55], v[54:55], v[70:71]
	v_pk_add_f32 v[52:53], v[52:53], v[78:79]
	v_mul_f32_e32 v59, v61, v61
	v_mul_f32_e32 v82, v63, v63
	v_pk_add_f32 v[70:71], v[50:51], v[72:73]
	v_pk_add_f32 v[72:73], v[48:49], v[80:81]
	v_mul_f32_e32 v48, v53, v53
	v_mul_f32_e32 v49, v55, v55
	v_mul_f32_e32 v83, v69, v69
	v_fmac_f32_e32 v59, v60, v60
	v_fmac_f32_e32 v82, v62, v62
	v_mul_f32_e32 v50, v73, v73
	v_fmac_f32_e32 v48, v52, v52
	v_fmac_f32_e32 v49, v54, v54
	v_mul_f32_e32 v84, v67, v67
	v_fmac_f32_e32 v83, v68, v68
	v_mul_f32_e32 v51, v71, v71
	v_add_f32_e32 v59, v59, v82
	v_fmac_f32_e32 v50, v72, v72
	v_add_f32_e32 v48, v48, v49
	v_fmac_f32_e32 v84, v66, v66
	v_add_f32_e32 v59, v83, v59
	v_add_f32_e32 v48, v50, v48
	v_fmac_f32_e32 v51, v70, v70
	v_add_f32_e32 v49, v84, v59
	v_add_f32_e32 v48, v51, v48
	v_add_f32_e32 v48, v49, v48
	ds_bpermute_b32 v49, v156, v48
	v_cvt_pk_bf16_f32 v56, v60, v61
	v_cvt_pk_bf16_f32 v57, v62, v63
	v_cvt_pk_bf16_f32 v58, v68, v69
	v_cvt_pk_bf16_f32 v59, v66, v67
	s_waitcnt lgkmcnt(0)
	v_add_f32_e32 v48, v48, v49
	ds_bpermute_b32 v49, v155, v48
	v_cvt_pk_bf16_f32 v50, v52, v53
	v_cvt_pk_bf16_f32 v51, v54, v55
	v_cvt_pk_bf16_f32 v52, v72, v73
	v_cvt_pk_bf16_f32 v53, v70, v71
	v_lshl_add_u64 v[54:55], s[10:11], 0, v[74:75]
	global_store_dwordx4 v[76:77], v[56:59], off
	global_store_dwordx4 v[54:55], v[50:53], off
	s_and_saveexec_b64 s[12:13], s[2:3]
	s_cbranch_execz .LBB0_1749
	v_lshl_add_u64 v[50:51], v[64:65], 2, s[14:15]
	s_waitcnt lgkmcnt(0)
	v_add_f32_e32 v48, v48, v49
	global_atomic_add_f32 v[50:51], v48, off
; DI unsigned pk2(float lo, float hi) { typedef float v2f __attribute__((ext_vector_type(2))); typedef __bf16 v2b __attribute__((ext_vector_type(2))); v2f v = {lo, hi}; v2b b = __builtin_convertvector(v, v2b); return __builtin_bit_cast(unsigned, b); }
; DI float bflo(unsigned w) { return __uint_as_float(w << 16); }
; DI float bfhi(unsigned w) { return __uint_as_float(w & 0xffff0000u); }
; DI void atomic_addf(float* p, float v) { __builtin_amdgcn_global_atomic_fadd_f32((__attribute__((address_space(1))) float*)p, v); }
; DI float quad_sum(float s) { s += __shfl_xor(s, 16); s += __shfl_xor(s, 32); return s; }
;     DI void operator()(const f32x4 (&acc)[2][2][4][2], const Unit& u, int wr, int wc, int fr, int fq) const {
;         const int row0 = u.pm * 256 + wr * 64 + fr, col0 = u.pn * 256 + wc * 32 + 8 * fq;
; #pragma unroll
;         for (int ai = 0; ai < 2; ++ai)
; #pragma unroll
;             for (int m = 0; m < 4; ++m) {
;                 const int row = row0 + ai * 128 + m * 16; float ss = 0.f;
;                 const float bs = (B16 && base) ? base[row] : 1.0f;
; #pragma unroll
;                 for (int bj = 0; bj < 2; ++bj) {
;                     const size_t off = (size_t)row * DM + col0 + bj * 128;
;                     f32x4 b0, b1;
;                     if (B16) { const u32x4 bb = *(const u32x4*)(base16 + off); b0 = (f32x4){bflo(bb.x), bfhi(bb.x), bflo(bb.y), bfhi(bb.y)}; b1 = (f32x4){bflo(bb.z), bfhi(bb.z), bflo(bb.w), bfhi(bb.w)}; b0 = b0 * bs; b1 = b1 * bs; }
;                     else { b0 = *(const f32x4*)(base + off); b1 = *(const f32x4*)(base + off + 4); }
;                     const f32x4 o0 = b0 + acc[ai][bj][m][0] * alpha, o1 = b1 + acc[ai][bj][m][1] * alpha;
;                     if (WOUT) { *(f32x4*)(out + off) = o0; *(f32x4*)(out + off + 4) = o1; }
;                     if (WB) { ss += (o0[0] * o0[0] + o0[1] * o0[1]) + (o0[2] * o0[2] + o0[3] * o0[3]) + (o1[0] * o1[0] + o1[1] * o1[1]) + (o1[2] * o1[2] + o1[3] * o1[3]);
;                         u32x4 w; w.x = pk2(o0[0], o0[1]); w.y = pk2(o0[2], o0[3]); w.z = pk2(o1[0], o1[1]); w.w = pk2(o1[2], o1[3]); *(u32x4*)(xb + off) = w; }
;                 }
;                 if (WB) { ss = quad_sum(ss); if (fq == 0) atomic_addf(P + row, ss); }
;             }
.LBB0_1749:
	s_or_b64 exec, exec, s[12:13]
	v_add_u32_e32 v48, 0x90, v146
	s_waitcnt lgkmcnt(0)
	v_ashrrev_i32_e32 v49, 31, v48
	v_lshlrev_b64 v[50:51], 10, v[48:49]
	v_lshl_add_u64 v[50:51], v[50:51], 0, v[144:145]
	v_lshlrev_b64 v[58:59], 1, v[50:51]
	v_lshl_add_u64 v[50:51], s[8:9], 0, v[58:59]
	v_lshl_add_u64 v[60:61], s[10:11], 0, v[58:59]
	v_or_b32_e32 v58, 0x100, v58
	s_nop 0
	v_lshl_add_u64 v[54:55], s[8:9], 0, v[58:59]
	s_nop 0
	v_lshlrev_b32_e32 v62, 16, v206
	v_and_b32_e32 v63, 0xffff0000, v206
	v_lshlrev_b32_e32 v50, 16, v207
	v_and_b32_e32 v51, 0xffff0000, v207
	v_lshlrev_b32_e32 v64, 16, v208
	v_and_b32_e32 v65, 0xffff0000, v208
	v_lshlrev_b32_e32 v52, 16, v209
	v_and_b32_e32 v53, 0xffff0000, v209
	v_pk_add_f32 v[44:45], v[44:45], v[62:63]
	v_lshlrev_b32_e32 v62, 16, v210
	v_and_b32_e32 v63, 0xffff0000, v210
	v_lshlrev_b32_e32 v54, 16, v211
	v_and_b32_e32 v55, 0xffff0000, v211
	v_pk_add_f32 v[46:47], v[46:47], v[50:51]
	v_pk_add_f32 v[50:51], v[42:43], v[52:53]
	v_pk_add_f32 v[52:53], v[40:41], v[64:65]
	v_lshlrev_b32_e32 v64, 16, v212
	v_and_b32_e32 v65, 0xffff0000, v212
	v_lshlrev_b32_e32 v56, 16, v213
	v_and_b32_e32 v57, 0xffff0000, v213
	v_pk_add_f32 v[38:39], v[38:39], v[54:55]
	v_pk_add_f32 v[36:37], v[36:37], v[62:63]
	v_mul_f32_e32 v43, v45, v45
	v_mul_f32_e32 v66, v47, v47
	v_pk_add_f32 v[54:55], v[34:35], v[56:57]
	v_pk_add_f32 v[56:57], v[32:33], v[64:65]
	v_mul_f32_e32 v32, v37, v37
	v_mul_f32_e32 v33, v39, v39
	v_mul_f32_e32 v67, v53, v53
	v_fmac_f32_e32 v43, v44, v44
	v_fmac_f32_e32 v66, v46, v46
	v_mul_f32_e32 v34, v57, v57
	v_fmac_f32_e32 v32, v36, v36
	v_fmac_f32_e32 v33, v38, v38
	v_mul_f32_e32 v68, v51, v51
	v_fmac_f32_e32 v67, v52, v52
	v_mul_f32_e32 v35, v55, v55
	v_add_f32_e32 v43, v43, v66
	v_fmac_f32_e32 v34, v56, v56
	v_add_f32_e32 v32, v32, v33
	v_fmac_f32_e32 v68, v50, v50
	v_add_f32_e32 v43, v67, v43
	v_add_f32_e32 v32, v34, v32
	v_fmac_f32_e32 v35, v54, v54
	v_add_f32_e32 v33, v68, v43
	v_add_f32_e32 v32, v35, v32
	v_add_f32_e32 v32, v33, v32
	ds_bpermute_b32 v33, v156, v32
	v_cvt_pk_bf16_f32 v40, v44, v45
	v_cvt_pk_bf16_f32 v41, v46, v47
	v_cvt_pk_bf16_f32 v42, v52, v53
	v_cvt_pk_bf16_f32 v43, v50, v51
	s_waitcnt lgkmcnt(0)
	v_add_f32_e32 v32, v32, v33
	ds_bpermute_b32 v33, v155, v32
	v_cvt_pk_bf16_f32 v34, v36, v37
	v_cvt_pk_bf16_f32 v35, v38, v39
	v_cvt_pk_bf16_f32 v36, v56, v57
	v_cvt_pk_bf16_f32 v37, v54, v55
	v_lshl_add_u64 v[38:39], s[10:11], 0, v[58:59]
	global_store_dwordx4 v[60:61], v[40:43], off
	global_store_dwordx4 v[38:39], v[34:37], off
	s_and_saveexec_b64 s[12:13], s[2:3]
	s_cbranch_execz .LBB0_1751
	v_lshl_add_u64 v[34:35], v[48:49], 2, s[14:15]
	s_waitcnt lgkmcnt(0)
	v_add_f32_e32 v32, v32, v33
	global_atomic_add_f32 v[34:35], v32, off
; DI unsigned pk2(float lo, float hi) { typedef float v2f __attribute__((ext_vector_type(2))); typedef __bf16 v2b __attribute__((ext_vector_type(2))); v2f v = {lo, hi}; v2b b = __builtin_convertvector(v, v2b); return __builtin_bit_cast(unsigned, b); }
; DI float bflo(unsigned w) { return __uint_as_float(w << 16); }
; DI float bfhi(unsigned w) { return __uint_as_float(w & 0xffff0000u); }
; DI void atomic_addf(float* p, float v) { __builtin_amdgcn_global_atomic_fadd_f32((__attribute__((address_space(1))) float*)p, v); }
; DI float quad_sum(float s) { s += __shfl_xor(s, 16); s += __shfl_xor(s, 32); return s; }
;     DI void operator()(const f32x4 (&acc)[2][2][4][2], const Unit& u, int wr, int wc, int fr, int fq) const {
;         const int row0 = u.pm * 256 + wr * 64 + fr, col0 = u.pn * 256 + wc * 32 + 8 * fq;
; #pragma unroll
;         for (int ai = 0; ai < 2; ++ai)
; #pragma unroll
;             for (int m = 0; m < 4; ++m) {
;                 const int row = row0 + ai * 128 + m * 16; float ss = 0.f;
;                 const float bs = (B16 && base) ? base[row] : 1.0f;
; #pragma unroll
;                 for (int bj = 0; bj < 2; ++bj) {
;                     const size_t off = (size_t)row * DM + col0 + bj * 128;
;                     f32x4 b0, b1;
;                     if (B16) { const u32x4 bb = *(const u32x4*)(base16 + off); b0 = (f32x4){bflo(bb.x), bfhi(bb.x), bflo(bb.y), bfhi(bb.y)}; b1 = (f32x4){bflo(bb.z), bfhi(bb.z), bflo(bb.w), bfhi(bb.w)}; b0 = b0 * bs; b1 = b1 * bs; }
;                     else { b0 = *(const f32x4*)(base + off); b1 = *(const f32x4*)(base + off + 4); }
;                     const f32x4 o0 = b0 + acc[ai][bj][m][0] * alpha, o1 = b1 + acc[ai][bj][m][1] * alpha;
;                     if (WOUT) { *(f32x4*)(out + off) = o0; *(f32x4*)(out + off + 4) = o1; }
;                     if (WB) { ss += (o0[0] * o0[0] + o0[1] * o0[1]) + (o0[2] * o0[2] + o0[3] * o0[3]) + (o1[0] * o1[0] + o1[1] * o1[1]) + (o1[2] * o1[2] + o1[3] * o1[3]);
;                         u32x4 w; w.x = pk2(o0[0], o0[1]); w.y = pk2(o0[2], o0[3]); w.z = pk2(o1[0], o1[1]); w.w = pk2(o1[2], o1[3]); *(u32x4*)(xb + off) = w; }
;                 }
;                 if (WB) { ss = quad_sum(ss); if (fq == 0) atomic_addf(P + row, ss); }
;             }
.LBB0_1751:
	s_or_b64 exec, exec, s[12:13]
	v_add_u32_e32 v32, 0xa0, v146
	s_waitcnt lgkmcnt(0)
	v_ashrrev_i32_e32 v33, 31, v32
	v_lshlrev_b64 v[34:35], 10, v[32:33]
	v_lshl_add_u64 v[34:35], v[34:35], 0, v[144:145]
	v_lshlrev_b64 v[42:43], 1, v[34:35]
	v_lshl_add_u64 v[34:35], s[8:9], 0, v[42:43]
	v_lshl_add_u64 v[44:45], s[10:11], 0, v[42:43]
	v_or_b32_e32 v42, 0x100, v42
	s_nop 0
	v_lshl_add_u64 v[38:39], s[8:9], 0, v[42:43]
	s_nop 0
	v_lshlrev_b32_e32 v46, 16, v214
	v_and_b32_e32 v47, 0xffff0000, v214
	v_lshlrev_b32_e32 v34, 16, v215
	v_and_b32_e32 v35, 0xffff0000, v215
	v_lshlrev_b32_e32 v48, 16, v216
	v_and_b32_e32 v49, 0xffff0000, v216
	v_lshlrev_b32_e32 v36, 16, v217
	v_and_b32_e32 v37, 0xffff0000, v217
	v_pk_add_f32 v[28:29], v[28:29], v[46:47]
	v_lshlrev_b32_e32 v46, 16, v218
	v_and_b32_e32 v47, 0xffff0000, v218
	v_lshlrev_b32_e32 v38, 16, v219
	v_and_b32_e32 v39, 0xffff0000, v219
	v_pk_add_f32 v[30:31], v[30:31], v[34:35]
	v_pk_add_f32 v[34:35], v[26:27], v[36:37]
	v_pk_add_f32 v[36:37], v[24:25], v[48:49]
	v_lshlrev_b32_e32 v48, 16, v220
	v_and_b32_e32 v49, 0xffff0000, v220
	v_lshlrev_b32_e32 v40, 16, v221
	v_and_b32_e32 v41, 0xffff0000, v221
	v_pk_add_f32 v[22:23], v[22:23], v[38:39]
	v_pk_add_f32 v[20:21], v[20:21], v[46:47]
	v_mul_f32_e32 v27, v29, v29
	v_mul_f32_e32 v50, v31, v31
	v_pk_add_f32 v[38:39], v[18:19], v[40:41]
	v_pk_add_f32 v[40:41], v[16:17], v[48:49]
	v_mul_f32_e32 v16, v21, v21
	v_mul_f32_e32 v17, v23, v23
	v_mul_f32_e32 v51, v37, v37
	v_fmac_f32_e32 v27, v28, v28
	v_fmac_f32_e32 v50, v30, v30
	v_mul_f32_e32 v18, v41, v41
	v_fmac_f32_e32 v16, v20, v20
	v_fmac_f32_e32 v17, v22, v22
	v_mul_f32_e32 v52, v35, v35
	v_fmac_f32_e32 v51, v36, v36
	v_mul_f32_e32 v19, v39, v39
	v_add_f32_e32 v27, v27, v50
	v_fmac_f32_e32 v18, v40, v40
	v_add_f32_e32 v16, v16, v17
	v_fmac_f32_e32 v52, v34, v34
	v_add_f32_e32 v27, v51, v27
	v_add_f32_e32 v16, v18, v16
	v_fmac_f32_e32 v19, v38, v38
	v_add_f32_e32 v17, v52, v27
	v_add_f32_e32 v16, v19, v16
	v_add_f32_e32 v16, v17, v16
	ds_bpermute_b32 v17, v156, v16
	v_cvt_pk_bf16_f32 v24, v28, v29
	v_cvt_pk_bf16_f32 v25, v30, v31
	v_cvt_pk_bf16_f32 v26, v36, v37
	v_cvt_pk_bf16_f32 v27, v34, v35
	s_waitcnt lgkmcnt(0)
	v_add_f32_e32 v16, v16, v17
	ds_bpermute_b32 v17, v155, v16
	v_cvt_pk_bf16_f32 v18, v20, v21
	v_cvt_pk_bf16_f32 v19, v22, v23
	v_cvt_pk_bf16_f32 v20, v40, v41
	v_cvt_pk_bf16_f32 v21, v38, v39
	v_lshl_add_u64 v[22:23], s[10:11], 0, v[42:43]
	global_store_dwordx4 v[44:45], v[24:27], off
	global_store_dwordx4 v[22:23], v[18:21], off
	s_and_saveexec_b64 s[12:13], s[2:3]
	s_cbranch_execz .LBB0_1753
	v_lshl_add_u64 v[18:19], v[32:33], 2, s[14:15]
	s_waitcnt lgkmcnt(0)
	v_add_f32_e32 v16, v16, v17
	global_atomic_add_f32 v[18:19], v16, off
.LBB0_1753:
	s_or_b64 exec, exec, s[12:13]
	v_add_u32_e32 v16, 0xb0, v146
	s_waitcnt lgkmcnt(0)
	v_ashrrev_i32_e32 v17, 31, v16
	v_lshlrev_b64 v[18:19], 10, v[16:17]
	v_lshl_add_u64 v[18:19], v[18:19], 0, v[144:145]
	v_lshlrev_b64 v[26:27], 1, v[18:19]
	v_lshl_add_u64 v[18:19], s[8:9], 0, v[26:27]
	v_lshl_add_u64 v[28:29], s[10:11], 0, v[26:27]
	v_or_b32_e32 v26, 0x100, v26
	s_nop 0
	v_lshl_add_u64 v[22:23], s[8:9], 0, v[26:27]
	s_nop 0
	v_lshlrev_b32_e32 v30, 16, v222
	v_and_b32_e32 v31, 0xffff0000, v222
	v_lshlrev_b32_e32 v18, 16, v223
	v_and_b32_e32 v19, 0xffff0000, v223
	v_lshlrev_b32_e32 v32, 16, v224
	v_and_b32_e32 v33, 0xffff0000, v224
	v_lshlrev_b32_e32 v20, 16, v225
	v_and_b32_e32 v21, 0xffff0000, v225
	v_pk_add_f32 v[12:13], v[12:13], v[30:31]
	v_lshlrev_b32_e32 v30, 16, v226
	v_and_b32_e32 v31, 0xffff0000, v226
	v_lshlrev_b32_e32 v22, 16, v227
	v_and_b32_e32 v23, 0xffff0000, v227
	v_pk_add_f32 v[14:15], v[14:15], v[18:19]
	v_pk_add_f32 v[18:19], v[10:11], v[20:21]
	v_pk_add_f32 v[20:21], v[8:9], v[32:33]
	v_lshlrev_b32_e32 v32, 16, v228
	v_and_b32_e32 v33, 0xffff0000, v228
	v_lshlrev_b32_e32 v24, 16, v229
	v_and_b32_e32 v25, 0xffff0000, v229
	v_pk_add_f32 v[6:7], v[6:7], v[22:23]
	v_pk_add_f32 v[4:5], v[4:5], v[30:31]
	v_mul_f32_e32 v11, v13, v13
	v_mul_f32_e32 v34, v15, v15
	v_pk_add_f32 v[22:23], v[2:3], v[24:25]
	v_pk_add_f32 v[24:25], v[0:1], v[32:33]
	v_mul_f32_e32 v0, v5, v5
	v_mul_f32_e32 v1, v7, v7
	v_mul_f32_e32 v35, v21, v21
	v_fmac_f32_e32 v11, v12, v12
	v_fmac_f32_e32 v34, v14, v14
	v_mul_f32_e32 v2, v25, v25
	v_fmac_f32_e32 v0, v4, v4
	v_fmac_f32_e32 v1, v6, v6
	v_mul_f32_e32 v36, v19, v19
	v_fmac_f32_e32 v35, v20, v20
	v_mul_f32_e32 v3, v23, v23
	v_add_f32_e32 v11, v11, v34
	v_fmac_f32_e32 v2, v24, v24
	v_add_f32_e32 v0, v0, v1
	v_fmac_f32_e32 v36, v18, v18
	v_add_f32_e32 v11, v35, v11
	v_add_f32_e32 v0, v2, v0
	v_fmac_f32_e32 v3, v22, v22
	v_add_f32_e32 v1, v36, v11
	v_add_f32_e32 v0, v3, v0
	v_add_f32_e32 v0, v1, v0
	ds_bpermute_b32 v1, v156, v0
	v_cvt_pk_bf16_f32 v8, v12, v13
	v_cvt_pk_bf16_f32 v9, v14, v15
	v_cvt_pk_bf16_f32 v10, v20, v21
	v_cvt_pk_bf16_f32 v11, v18, v19
	s_waitcnt lgkmcnt(0)
	v_add_f32_e32 v0, v0, v1
	ds_bpermute_b32 v1, v155, v0
	v_cvt_pk_bf16_f32 v2, v4, v5
	v_cvt_pk_bf16_f32 v3, v6, v7
	v_cvt_pk_bf16_f32 v4, v24, v25
	v_cvt_pk_bf16_f32 v5, v22, v23
	v_lshl_add_u64 v[6:7], s[10:11], 0, v[26:27]
	global_store_dwordx4 v[28:29], v[8:11], off
	global_store_dwordx4 v[6:7], v[2:5], off
	s_and_saveexec_b64 s[12:13], s[2:3]
	s_cbranch_execz .LBB0_1755
	v_lshl_add_u64 v[2:3], v[16:17], 2, s[14:15]
	s_waitcnt lgkmcnt(0)
	v_add_f32_e32 v0, v0, v1
	global_atomic_add_f32 v[2:3], v0, off
